# saddr-form K-loop DMAs (no 64-bit VALU address adds in the R phases) stacked with early end-of-M barrier + tight handoff
# speedup vs baseline: 1.0065x; 1.0065x over previous
; #define PG8_STAGE(bufoff, gbase, voff) do { _Pragma("unroll") for (int _i = 0; _i < 2; ++_i) \
;         __builtin_amdgcn_global_load_lds((const unsigned*)((const char*)(gbase) + (voff)[_i]), (LAS unsigned*)(lds + (bufoff) + ldsw + _i * 8192), 16, 0, 0); } while (0)
; #define PG8_LDA(dst, b, h) do { _Pragma("unroll") for (int m = 0; m < 4; ++m) _Pragma("unroll") for (int k = 0; k < 2; ++k) dst[m][k] = *(const LAS bf16x8*)(lds + PG8_SA(b, h) + aoff + m * 2048 + k * 1024); } while (0)
; #define PG8_LDB(dst, b, h) do { _Pragma("unroll") for (int n = 0; n < 2; ++n) _Pragma("unroll") for (int k = 0; k < 2; ++k) dst[n][k] = *(const LAS bf16x8*)(lds + PG8_SB(b, h) + boff + n * 2048 + k * 1024); } while (0)
; #define PG8_MMA(ai, bj, At, Bt) do { __builtin_amdgcn_s_setprio(3); _Pragma("unroll") for (int m = 0; m < 4; ++m) _Pragma("unroll") for (int n = 0; n < 2; ++n) _Pragma("unroll") for (int k = 0; k < 2; ++k) \
;         acc[ai][bj][m][n] = __builtin_amdgcn_mfma_f32_16x16x32_bf16(Bt[n][k], At[m][k], acc[ai][bj][m][n], 0, 0, 0); __builtin_amdgcn_s_setprio(0); } while (0)
; #define PG8_WAIT_V(n) asm volatile("s_waitcnt vmcnt(" #n ")" ::: "memory")
; #define PG8_BAR __builtin_amdgcn_s_barrier()
; template <class Epi, class Sched, bool ALIGN_EPI = false, bool SP2 = false>
; __device__ __forceinline__ void gemm_phase(LAS unsigned char* lds, const Gemm g, const Sched& S, const Epi& E) {
;     ...
;             const bool last = (t == nt - 2);
;             const char* a1 = cA + (size_t)(t + 1) * kstep;
;             const char* a2 = last ? nA : cA + (size_t)(t + 2) * kstep; const char* b2 = last ? nB : cB + (size_t)(t + 2) * kstep;
;             const char* a3 = a2 + kstep; const char* b3 = b2 + kstep;
;             if (last && has_next) S.a_ready(nxt);
;             if constexpr (Epi::MID) { if (t == nt / 2) E.mid(acc, cur, wr, wc, fr, fq); }
;             if constexpr (SP2) {
;             PG8_LDB(B0, 0, 0); PG8_LDB(B1, 0, 1); PG8_SCHED; PG8_LDA(At, 0, 0); PG8_STAGE(PG8_SA(1, 1), a1 + hsA, voffA);
;             PG8_WAIT_V(8); PG8_WAIT_L(0); PG8_BAR; PG8_MMA(0, 0, At, B0); PG8_MMA(0, 1, At, B1); PG8_BAR; PG8_SCHED;
;             PG8_LDA(At, 0, 1); PG8_STAGE(PG8_SB(0, 0), b2, voffB); PG8_STAGE(PG8_SB(0, 1), b2 + hsB, voffB); PG8_STAGE(PG8_SA(0, 0), a2, voffA);
;             PG8_WAIT_V(8); PG8_WAIT_L(0); PG8_BAR; PG8_MMA(1, 0, At, B0); PG8_MMA(1, 1, At, B1); PG8_BAR; PG8_SCHED;
.LBB0_64:
	ds_read_b128 v[128:131], v158
	ds_read_b128 v[150:153], v251
	ds_read_b128 v[166:169], v158 offset:2048
	ds_read_b128 v[170:173], v251 offset:2048
	ds_read_b128 v[174:177], v159
	ds_read_b128 v[178:181], v252
	ds_read_b128 v[182:185], v159 offset:2048
	ds_read_b128 v[186:189], v252 offset:2048
	s_add_u32 s6, s4, 0xffefc080
	s_addc_u32 s7, s5, -1
	s_cmp_eq_u32 s91, 60
	s_cselect_b32 s63, s59, s7
	s_cselect_b32 s62, s58, s6
	s_cselect_b32 s7, s61, s90
	s_cselect_b32 s6, s60, s89
	s_sub_u32 s100, s4, 0x104000
	s_subb_u32 s101, s5, 0
	s_mov_b32 m0, s76
	s_nop 0
	global_load_lds_dwordx4 v132, s[100:101]
	s_mov_b32 m0, s77
	s_nop 0
	global_load_lds_dwordx4 v136, s[100:101]
	s_add_i32 m0, s68, 0xc000
	ds_read_b128 v[190:193], v160
	ds_read_b128 v[194:197], v250
	ds_read_b128 v[198:201], v160 offset:2048
	ds_read_b128 v[206:209], v250 offset:2048
	ds_read_b128 v[210:213], v160 offset:4096
	ds_read_b128 v[214:217], v250 offset:4096
	ds_read_b128 v[218:221], v160 offset:6144
	ds_read_b128 v[222:225], v250 offset:6144
	global_load_lds_dwordx4 v142, s[4:5]
	s_add_i32 m0, s68, 0xe000
	s_nop 0
	global_load_lds_dwordx4 v144, s[4:5]
	s_waitcnt vmcnt(8)
	s_waitcnt lgkmcnt(0)
	s_setprio 2
	s_barrier
	v_mfma_f32_16x16x32_bf16 v[124:127], v[128:131], v[190:193], v[124:127]
	v_mfma_f32_16x16x32_bf16 v[124:127], v[150:153], v[194:197], v[124:127]
	v_mfma_f32_16x16x32_bf16 v[120:123], v[166:169], v[190:193], v[120:123]
	v_mfma_f32_16x16x32_bf16 v[120:123], v[170:173], v[194:197], v[120:123]
	v_mfma_f32_16x16x32_bf16 v[108:111], v[128:131], v[198:201], v[108:111]
	v_mfma_f32_16x16x32_bf16 v[108:111], v[150:153], v[206:209], v[108:111]
	v_mfma_f32_16x16x32_bf16 v[104:107], v[166:169], v[198:201], v[104:107]
	v_mfma_f32_16x16x32_bf16 v[104:107], v[170:173], v[206:209], v[104:107]
	v_mfma_f32_16x16x32_bf16 v[92:95], v[128:131], v[210:213], v[92:95]
	v_mfma_f32_16x16x32_bf16 v[92:95], v[150:153], v[214:217], v[92:95]
	v_mfma_f32_16x16x32_bf16 v[88:91], v[166:169], v[210:213], v[88:91]
	v_mfma_f32_16x16x32_bf16 v[88:91], v[170:173], v[214:217], v[88:91]
	v_mfma_f32_16x16x32_bf16 v[76:79], v[128:131], v[218:221], v[76:79]
	v_mfma_f32_16x16x32_bf16 v[76:79], v[150:153], v[222:225], v[76:79]
	v_mfma_f32_16x16x32_bf16 v[72:75], v[166:169], v[218:221], v[72:75]
	v_mfma_f32_16x16x32_bf16 v[72:75], v[170:173], v[222:225], v[72:75]
	s_setprio 0
	s_setprio 2
	v_mfma_f32_16x16x32_bf16 v[116:119], v[174:177], v[190:193], v[116:119]
	v_mfma_f32_16x16x32_bf16 v[116:119], v[178:181], v[194:197], v[116:119]
	v_mfma_f32_16x16x32_bf16 v[112:115], v[182:185], v[190:193], v[112:115]
	v_mfma_f32_16x16x32_bf16 v[112:115], v[186:189], v[194:197], v[112:115]
	v_mfma_f32_16x16x32_bf16 v[100:103], v[174:177], v[198:201], v[100:103]
	v_mfma_f32_16x16x32_bf16 v[100:103], v[178:181], v[206:209], v[100:103]
	v_mfma_f32_16x16x32_bf16 v[96:99], v[182:185], v[198:201], v[96:99]
	v_mfma_f32_16x16x32_bf16 v[96:99], v[186:189], v[206:209], v[96:99]
	v_mfma_f32_16x16x32_bf16 v[84:87], v[174:177], v[210:213], v[84:87]
	v_mfma_f32_16x16x32_bf16 v[84:87], v[178:181], v[214:217], v[84:87]
	v_mfma_f32_16x16x32_bf16 v[80:83], v[182:185], v[210:213], v[80:83]
	v_mfma_f32_16x16x32_bf16 v[80:83], v[186:189], v[214:217], v[80:83]
	v_mfma_f32_16x16x32_bf16 v[68:71], v[174:177], v[218:221], v[68:71]
	v_mfma_f32_16x16x32_bf16 v[68:71], v[178:181], v[222:225], v[68:71]
	v_mfma_f32_16x16x32_bf16 v[64:67], v[182:185], v[218:221], v[64:67]
	s_setprio 3
	s_barrier
	v_mfma_f32_16x16x32_bf16 v[64:67], v[186:189], v[222:225], v[64:67]
	s_setprio 0
	s_add_i32 s92, s82, s67
	s_mov_b32 m0, s92
	ds_read_b128 v[190:193], v160 offset:16384
	ds_read_b128 v[194:197], v250 offset:16384
	ds_read_b128 v[198:201], v160 offset:18432
	ds_read_b128 v[206:209], v250 offset:18432
	ds_read_b128 v[210:213], v160 offset:20480
	ds_read_b128 v[214:217], v250 offset:20480
	ds_read_b128 v[218:221], v160 offset:22528
	ds_read_b128 v[222:225], v250 offset:22528
	global_load_lds_dwordx4 v134, s[6:7]
	s_add_i32 m0, s92, 0x2000
	s_add_u32 s92, s6, 0x41000
	s_addc_u32 s93, s7, 0
	s_add_i32 s94, s83, s67
	global_load_lds_dwordx4 v138, s[6:7]
	s_mov_b32 m0, s94
	s_nop 0
	global_load_lds_dwordx4 v134, s[92:93]
	s_add_i32 m0, s94, 0x2000
	s_nop 0
	global_load_lds_dwordx4 v138, s[92:93]
	s_waitcnt vmcnt(6)
	s_waitcnt lgkmcnt(0)
	s_setprio 2
	s_barrier
	v_mfma_f32_16x16x32_bf16 v[60:63], v[128:131], v[190:193], v[60:63]
	v_mfma_f32_16x16x32_bf16 v[60:63], v[150:153], v[194:197], v[60:63]
	v_mfma_f32_16x16x32_bf16 v[56:59], v[166:169], v[190:193], v[56:59]
	v_mfma_f32_16x16x32_bf16 v[56:59], v[170:173], v[194:197], v[56:59]
	v_mfma_f32_16x16x32_bf16 v[44:47], v[128:131], v[198:201], v[44:47]
	v_mfma_f32_16x16x32_bf16 v[44:47], v[150:153], v[206:209], v[44:47]
	v_mfma_f32_16x16x32_bf16 v[40:43], v[166:169], v[198:201], v[40:43]
	v_mfma_f32_16x16x32_bf16 v[40:43], v[170:173], v[206:209], v[40:43]
	v_mfma_f32_16x16x32_bf16 v[28:31], v[128:131], v[210:213], v[28:31]
	v_mfma_f32_16x16x32_bf16 v[28:31], v[150:153], v[214:217], v[28:31]
	v_mfma_f32_16x16x32_bf16 v[24:27], v[166:169], v[210:213], v[24:27]
	v_mfma_f32_16x16x32_bf16 v[24:27], v[170:173], v[214:217], v[24:27]
	v_mfma_f32_16x16x32_bf16 v[12:15], v[128:131], v[218:221], v[12:15]
	v_mfma_f32_16x16x32_bf16 v[12:15], v[150:153], v[222:225], v[12:15]
	v_mfma_f32_16x16x32_bf16 v[8:11], v[166:169], v[218:221], v[8:11]
	v_mfma_f32_16x16x32_bf16 v[8:11], v[170:173], v[222:225], v[8:11]
	s_setprio 0
	s_setprio 2
	v_mfma_f32_16x16x32_bf16 v[52:55], v[174:177], v[190:193], v[52:55]
	v_mfma_f32_16x16x32_bf16 v[52:55], v[178:181], v[194:197], v[52:55]
	v_mfma_f32_16x16x32_bf16 v[48:51], v[182:185], v[190:193], v[48:51]
	v_mfma_f32_16x16x32_bf16 v[48:51], v[186:189], v[194:197], v[48:51]
	v_mfma_f32_16x16x32_bf16 v[36:39], v[174:177], v[198:201], v[36:39]
	v_mfma_f32_16x16x32_bf16 v[36:39], v[178:181], v[206:209], v[36:39]
	v_mfma_f32_16x16x32_bf16 v[32:35], v[182:185], v[198:201], v[32:35]
	v_mfma_f32_16x16x32_bf16 v[32:35], v[186:189], v[206:209], v[32:35]
	v_mfma_f32_16x16x32_bf16 v[20:23], v[174:177], v[210:213], v[20:23]
	v_mfma_f32_16x16x32_bf16 v[20:23], v[178:181], v[214:217], v[20:23]
	v_mfma_f32_16x16x32_bf16 v[16:19], v[182:185], v[210:213], v[16:19]
	v_mfma_f32_16x16x32_bf16 v[16:19], v[186:189], v[214:217], v[16:19]
	v_mfma_f32_16x16x32_bf16 v[4:7], v[174:177], v[218:221], v[4:7]
	v_mfma_f32_16x16x32_bf16 v[4:7], v[178:181], v[222:225], v[4:7]
	v_mfma_f32_16x16x32_bf16 v[0:3], v[182:185], v[218:221], v[0:3]
	s_setprio 3
	s_barrier
; #define PG8_STAGE(bufoff, gbase, voff) do { _Pragma("unroll") for (int _i = 0; _i < 2; ++_i) \
;         __builtin_amdgcn_global_load_lds((const unsigned*)((const char*)(gbase) + (voff)[_i]), (LAS unsigned*)(lds + (bufoff) + ldsw + _i * 8192), 16, 0, 0); } while (0)
; #define PG8_LDA(dst, b, h) do { _Pragma("unroll") for (int m = 0; m < 4; ++m) _Pragma("unroll") for (int k = 0; k < 2; ++k) dst[m][k] = *(const LAS bf16x8*)(lds + PG8_SA(b, h) + aoff + m * 2048 + k * 1024); } while (0)
; #define PG8_LDB(dst, b, h) do { _Pragma("unroll") for (int n = 0; n < 2; ++n) _Pragma("unroll") for (int k = 0; k < 2; ++k) dst[n][k] = *(const LAS bf16x8*)(lds + PG8_SB(b, h) + boff + n * 2048 + k * 1024); } while (0)
; #define PG8_MMA(ai, bj, At, Bt) do { __builtin_amdgcn_s_setprio(3); _Pragma("unroll") for (int m = 0; m < 4; ++m) _Pragma("unroll") for (int n = 0; n < 2; ++n) _Pragma("unroll") for (int k = 0; k < 2; ++k) \
;         acc[ai][bj][m][n] = __builtin_amdgcn_mfma_f32_16x16x32_bf16(Bt[n][k], At[m][k], acc[ai][bj][m][n], 0, 0, 0); __builtin_amdgcn_s_setprio(0); } while (0)
; #define PG8_WAIT_V(n) asm volatile("s_waitcnt vmcnt(" #n ")" ::: "memory")
; #define PG8_WAIT_L(n) asm volatile("s_waitcnt lgkmcnt(" #n ")" ::: "memory")
; #define PG8_BAR __builtin_amdgcn_s_barrier()
; #define PG8_SCHED __builtin_amdgcn_sched_barrier(0)
; template <class Epi, class Sched, bool ALIGN_EPI = false, bool SP2 = false>
; __device__ __forceinline__ void gemm_phase(LAS unsigned char* lds, const Gemm g, const Sched& S, const Epi& E) {
;     ...
;             PG8_WAIT_V(8); PG8_WAIT_L(0); PG8_BAR; PG8_MMA(1, 0, At, B0); PG8_MMA(1, 1, At, B1); PG8_BAR; PG8_SCHED;
;             PG8_LDB(B0, 1, 0); PG8_LDB(B1, 1, 1); PG8_SCHED; PG8_LDA(At, 1, 0); PG8_STAGE(PG8_SA(0, 1), a2 + hsA, voffA);
;             PG8_WAIT_V(8); PG8_WAIT_L(0); PG8_BAR; PG8_MMA(0, 0, At, B0); PG8_MMA(0, 1, At, B1); PG8_BAR; PG8_SCHED;
;             PG8_LDA(At, 1, 1); PG8_STAGE(PG8_SB(1, 0), b3, voffB); PG8_STAGE(PG8_SB(1, 1), b3 + hsB, voffB); PG8_STAGE(PG8_SA(1, 0), a3, voffA);
;             PG8_WAIT_V(8); PG8_WAIT_L(0); PG8_BAR; PG8_MMA(1, 0, At, B0); PG8_MMA(1, 1, At, B1); PG8_BAR; PG8_SCHED;
;     ...
;         if constexpr (ALIGN_EPI) { if (wr == 0) PG8_BAR; }
	v_mfma_f32_16x16x32_bf16 v[0:3], v[186:189], v[222:225], v[0:3]
	s_setprio 0
	s_add_i32 s92, 0, 0x18000
	v_add_u32_e32 v165, s92, v156
	v_xor_b32_e32 v253, 64, v165
	s_add_i32 s93, 0, 0x1c000
	ds_read_b128 v[128:131], v165
	ds_read_b128 v[150:153], v253
	ds_read_b128 v[166:169], v165 offset:2048
	ds_read_b128 v[170:173], v253 offset:2048
	v_add_u32_e32 v165, s93, v156
	v_xor_b32_e32 v253, 64, v165
	ds_read_b128 v[174:177], v165
	ds_read_b128 v[178:181], v253
	ds_read_b128 v[182:185], v165 offset:2048
	ds_read_b128 v[186:189], v253 offset:2048
	s_mov_b32 m0, s68
	s_nop 0
	global_load_lds_dwordx4 v132, s[62:63]
	s_mov_b32 m0, s69
	s_nop 0
	global_load_lds_dwordx4 v136, s[62:63]
	s_add_u32 s62, s62, 0x104000
	s_addc_u32 s63, s63, 0
	s_mov_b32 m0, s70
	ds_read_b128 v[190:193], v160 offset:32768
	ds_read_b128 v[194:197], v250 offset:32768
	ds_read_b128 v[198:201], v160 offset:34816
	ds_read_b128 v[206:209], v250 offset:34816
	ds_read_b128 v[210:213], v160 offset:36864
	ds_read_b128 v[214:217], v250 offset:36864
	ds_read_b128 v[218:221], v160 offset:38912
	ds_read_b128 v[222:225], v250 offset:38912
	global_load_lds_dwordx4 v132, s[62:63]
	s_mov_b32 m0, s71
	s_nop 0
	global_load_lds_dwordx4 v136, s[62:63]
	s_waitcnt vmcnt(8)
	s_waitcnt lgkmcnt(0)
	s_setprio 2
	s_barrier
	v_mfma_f32_16x16x32_bf16 v[124:127], v[128:131], v[190:193], v[124:127]
	v_mfma_f32_16x16x32_bf16 v[124:127], v[150:153], v[194:197], v[124:127]
	v_mfma_f32_16x16x32_bf16 v[120:123], v[166:169], v[190:193], v[120:123]
	v_mfma_f32_16x16x32_bf16 v[120:123], v[170:173], v[194:197], v[120:123]
	v_mfma_f32_16x16x32_bf16 v[108:111], v[128:131], v[198:201], v[108:111]
	v_mfma_f32_16x16x32_bf16 v[108:111], v[150:153], v[206:209], v[108:111]
	v_mfma_f32_16x16x32_bf16 v[104:107], v[166:169], v[198:201], v[104:107]
	v_mfma_f32_16x16x32_bf16 v[104:107], v[170:173], v[206:209], v[104:107]
	v_mfma_f32_16x16x32_bf16 v[92:95], v[128:131], v[210:213], v[92:95]
	v_mfma_f32_16x16x32_bf16 v[92:95], v[150:153], v[214:217], v[92:95]
	v_mfma_f32_16x16x32_bf16 v[88:91], v[166:169], v[210:213], v[88:91]
	v_mfma_f32_16x16x32_bf16 v[88:91], v[170:173], v[214:217], v[88:91]
	v_mfma_f32_16x16x32_bf16 v[76:79], v[128:131], v[218:221], v[76:79]
	v_mfma_f32_16x16x32_bf16 v[76:79], v[150:153], v[222:225], v[76:79]
	v_mfma_f32_16x16x32_bf16 v[72:75], v[166:169], v[218:221], v[72:75]
	v_mfma_f32_16x16x32_bf16 v[72:75], v[170:173], v[222:225], v[72:75]
	s_setprio 0
	s_setprio 2
	v_mfma_f32_16x16x32_bf16 v[116:119], v[174:177], v[190:193], v[116:119]
	v_mfma_f32_16x16x32_bf16 v[116:119], v[178:181], v[194:197], v[116:119]
	v_mfma_f32_16x16x32_bf16 v[112:115], v[182:185], v[190:193], v[112:115]
	v_mfma_f32_16x16x32_bf16 v[112:115], v[186:189], v[194:197], v[112:115]
	v_mfma_f32_16x16x32_bf16 v[100:103], v[174:177], v[198:201], v[100:103]
	v_mfma_f32_16x16x32_bf16 v[100:103], v[178:181], v[206:209], v[100:103]
	v_mfma_f32_16x16x32_bf16 v[96:99], v[182:185], v[198:201], v[96:99]
	v_mfma_f32_16x16x32_bf16 v[96:99], v[186:189], v[206:209], v[96:99]
	v_mfma_f32_16x16x32_bf16 v[84:87], v[174:177], v[210:213], v[84:87]
	v_mfma_f32_16x16x32_bf16 v[84:87], v[178:181], v[214:217], v[84:87]
	v_mfma_f32_16x16x32_bf16 v[80:83], v[182:185], v[210:213], v[80:83]
	v_mfma_f32_16x16x32_bf16 v[80:83], v[186:189], v[214:217], v[80:83]
	v_mfma_f32_16x16x32_bf16 v[68:71], v[174:177], v[218:221], v[68:71]
	v_mfma_f32_16x16x32_bf16 v[68:71], v[178:181], v[222:225], v[68:71]
	v_mfma_f32_16x16x32_bf16 v[64:67], v[182:185], v[218:221], v[64:67]
	s_setprio 3
	s_barrier
	v_mfma_f32_16x16x32_bf16 v[64:67], v[186:189], v[222:225], v[64:67]
	s_setprio 0
	s_add_i32 s62, s92, s67
	s_add_u32 s100, s6, s46
	s_addc_u32 s101, s7, s47
	s_mov_b32 m0, s62
	ds_read_b128 v[190:193], v160 offset:49152
	ds_read_b128 v[194:197], v250 offset:49152
	ds_read_b128 v[198:201], v160 offset:51200
	ds_read_b128 v[206:209], v250 offset:51200
	ds_read_b128 v[210:213], v160 offset:53248
	ds_read_b128 v[214:217], v250 offset:53248
	ds_read_b128 v[218:221], v160 offset:55296
	ds_read_b128 v[222:225], v250 offset:55296
	global_load_lds_dwordx4 v134, s[100:101]
	s_add_i32 m0, s62, 0x2000
	s_add_u32 s6, s6, 0x41080
	s_addc_u32 s7, s7, 0
	s_add_i32 s62, s93, s67
	global_load_lds_dwordx4 v138, s[100:101]
	s_mov_b32 m0, s62
	s_nop 0
	global_load_lds_dwordx4 v134, s[6:7]
	s_add_i32 m0, s62, 0x2000
	s_nop 0
	global_load_lds_dwordx4 v138, s[6:7]
	s_waitcnt vmcnt(6)
	s_waitcnt lgkmcnt(0)
	s_setprio 2
	s_barrier
	v_mfma_f32_16x16x32_bf16 v[60:63], v[128:131], v[190:193], v[60:63]
	v_mfma_f32_16x16x32_bf16 v[60:63], v[150:153], v[194:197], v[60:63]
	v_mfma_f32_16x16x32_bf16 v[56:59], v[166:169], v[190:193], v[56:59]
	v_mfma_f32_16x16x32_bf16 v[56:59], v[170:173], v[194:197], v[56:59]
	v_mfma_f32_16x16x32_bf16 v[44:47], v[128:131], v[198:201], v[44:47]
	v_mfma_f32_16x16x32_bf16 v[44:47], v[150:153], v[206:209], v[44:47]
	v_mfma_f32_16x16x32_bf16 v[40:43], v[166:169], v[198:201], v[40:43]
	v_mfma_f32_16x16x32_bf16 v[40:43], v[170:173], v[206:209], v[40:43]
	v_mfma_f32_16x16x32_bf16 v[28:31], v[128:131], v[210:213], v[28:31]
	v_mfma_f32_16x16x32_bf16 v[28:31], v[150:153], v[214:217], v[28:31]
	v_mfma_f32_16x16x32_bf16 v[24:27], v[166:169], v[210:213], v[24:27]
	v_mfma_f32_16x16x32_bf16 v[24:27], v[170:173], v[214:217], v[24:27]
	v_mfma_f32_16x16x32_bf16 v[12:15], v[128:131], v[218:221], v[12:15]
	v_mfma_f32_16x16x32_bf16 v[12:15], v[150:153], v[222:225], v[12:15]
	v_mfma_f32_16x16x32_bf16 v[8:11], v[166:169], v[218:221], v[8:11]
	v_mfma_f32_16x16x32_bf16 v[8:11], v[170:173], v[222:225], v[8:11]
	s_setprio 0
	s_setprio 2
	v_mfma_f32_16x16x32_bf16 v[52:55], v[174:177], v[190:193], v[52:55]
	v_mfma_f32_16x16x32_bf16 v[52:55], v[178:181], v[194:197], v[52:55]
	v_mfma_f32_16x16x32_bf16 v[48:51], v[182:185], v[190:193], v[48:51]
	v_mfma_f32_16x16x32_bf16 v[48:51], v[186:189], v[194:197], v[48:51]
	v_mfma_f32_16x16x32_bf16 v[36:39], v[174:177], v[198:201], v[36:39]
	v_mfma_f32_16x16x32_bf16 v[36:39], v[178:181], v[206:209], v[36:39]
	v_mfma_f32_16x16x32_bf16 v[32:35], v[182:185], v[198:201], v[32:35]
	v_mfma_f32_16x16x32_bf16 v[32:35], v[186:189], v[206:209], v[32:35]
	v_mfma_f32_16x16x32_bf16 v[20:23], v[174:177], v[210:213], v[20:23]
	v_mfma_f32_16x16x32_bf16 v[20:23], v[178:181], v[214:217], v[20:23]
	v_mfma_f32_16x16x32_bf16 v[16:19], v[182:185], v[210:213], v[16:19]
	v_mfma_f32_16x16x32_bf16 v[16:19], v[186:189], v[214:217], v[16:19]
	v_mfma_f32_16x16x32_bf16 v[4:7], v[174:177], v[218:221], v[4:7]
	v_mfma_f32_16x16x32_bf16 v[4:7], v[178:181], v[222:225], v[4:7]
	v_mfma_f32_16x16x32_bf16 v[0:3], v[182:185], v[218:221], v[0:3]
	s_setprio 3
	s_barrier
	v_mfma_f32_16x16x32_bf16 v[0:3], v[186:189], v[222:225], v[0:3]
	s_setprio 0
	s_add_i32 s91, s91, 2
	s_add_u32 s4, s4, 0x100
	s_addc_u32 s5, s5, 0
	s_add_u32 s89, s89, 0x100
	s_addc_u32 s90, s90, 0
	s_cmp_gt_u32 s91, 61
	s_cbranch_scc0 .LBB0_64
	s_and_b64 vcc, exec, s[50:51]
	s_cbranch_vccz .LBB0_67
	s_barrier

; #define PG8_STAGE(bufoff, gbase, voff) do { _Pragma("unroll") for (int _i = 0; _i < 2; ++_i) \
;         __builtin_amdgcn_global_load_lds((const unsigned*)((const char*)(gbase) + (voff)[_i]), (LAS unsigned*)(lds + (bufoff) + ldsw + _i * 8192), 16, 0, 0); } while (0)
; #define PG8_LDA(dst, b, h) do { _Pragma("unroll") for (int m = 0; m < 4; ++m) _Pragma("unroll") for (int k = 0; k < 2; ++k) dst[m][k] = *(const LAS bf16x8*)(lds + PG8_SA(b, h) + aoff + m * 2048 + k * 1024); } while (0)
; #define PG8_LDB(dst, b, h) do { _Pragma("unroll") for (int n = 0; n < 2; ++n) _Pragma("unroll") for (int k = 0; k < 2; ++k) dst[n][k] = *(const LAS bf16x8*)(lds + PG8_SB(b, h) + boff + n * 2048 + k * 1024); } while (0)
; #define PG8_MMA(ai, bj, At, Bt) do { __builtin_amdgcn_s_setprio(3); _Pragma("unroll") for (int m = 0; m < 4; ++m) _Pragma("unroll") for (int n = 0; n < 2; ++n) _Pragma("unroll") for (int k = 0; k < 2; ++k) \
;         acc[ai][bj][m][n] = __builtin_amdgcn_mfma_f32_16x16x32_bf16(Bt[n][k], At[m][k], acc[ai][bj][m][n], 0, 0, 0); __builtin_amdgcn_s_setprio(0); } while (0)
; #define PG8_WAIT_V(n) asm volatile("s_waitcnt vmcnt(" #n ")" ::: "memory")
; #define PG8_WAIT_L(n) asm volatile("s_waitcnt lgkmcnt(" #n ")" ::: "memory")
; #define PG8_BAR __builtin_amdgcn_s_barrier()
; template <class Epi, class Sched, bool ALIGN_EPI = false, bool SP2 = false>
; __device__ __forceinline__ void gemm_phase(LAS unsigned char* lds, const Gemm g, const Sched& S, const Epi& E) {
;     ...
;             const bool last = (t == nt - 2);
;             const char* a1 = cA + (size_t)(t + 1) * kstep;
;             const char* a2 = last ? nA : cA + (size_t)(t + 2) * kstep; const char* b2 = last ? nB : cB + (size_t)(t + 2) * kstep;
;             const char* a3 = a2 + kstep; const char* b3 = b2 + kstep;
;             if (last && has_next) S.a_ready(nxt);
;             if constexpr (Epi::MID) { if (t == nt / 2) E.mid(acc, cur, wr, wc, fr, fq); }
;             if constexpr (SP2) {
;             PG8_LDB(B0, 0, 0); PG8_LDB(B1, 0, 1); PG8_SCHED; PG8_LDA(At, 0, 0); PG8_STAGE(PG8_SA(1, 1), a1 + hsA, voffA);
;             PG8_WAIT_V(8); PG8_WAIT_L(0); PG8_BAR; PG8_MMA(0, 0, At, B0); PG8_MMA(0, 1, At, B1); PG8_BAR; PG8_SCHED;
;             PG8_LDA(At, 0, 1); PG8_STAGE(PG8_SB(0, 0), b2, voffB); PG8_STAGE(PG8_SB(0, 1), b2 + hsB, voffB); PG8_STAGE(PG8_SA(0, 0), a2, voffA);
.LBB0_234:
	v_add_u32_e32 v1, s88, v194
	v_xor_b32_e32 v253, 64, v1
	ds_read_b128 v[84:87], v1
	ds_read_b128 v[96:99], v253
	ds_read_b128 v[140:143], v1 offset:2048
	ds_read_b128 v[144:147], v253 offset:2048
	v_add_u32_e32 v1, s89, v194
	v_xor_b32_e32 v253, 64, v1
	s_add_u32 s4, s64, s66
	ds_read_b128 v[152:155], v1
	ds_read_b128 v[156:159], v253
	ds_read_b128 v[160:163], v1 offset:2048
	ds_read_b128 v[182:185], v253 offset:2048
	s_addc_u32 s5, s65, s67
	s_add_u32 s4, s4, 0x100
	s_addc_u32 s5, s5, 0
	s_add_u32 s96, s93, s66
	s_addc_u32 s97, s94, s67
	s_cmpk_eq_i32 s66, 0x1f00
	s_cselect_b32 s9, s59, s5
	s_cselect_b32 s8, s91, s4
	s_cselect_b32 s5, s61, s97
	s_cselect_b32 s4, s60, s96
	s_sub_u32 s100, s66, 0x100000
	s_subb_u32 s101, s67, 0
	v_lshl_add_u64 v[242:243], v[148:149], 0, s[100:101]
	s_mov_b32 m0, s81
	v_lshl_add_u64 v[244:245], v[150:151], 0, s[100:101]
	global_load_lds_dwordx4 v[242:243], off
	s_mov_b32 m0, s82
	s_nop 0
	global_load_lds_dwordx4 v[244:245], off
	v_lshl_add_u64 v[2:3], v[148:149], 0, s[66:67]
	s_add_i32 m0, s41, 0xc000
	ds_read_b128 v[186:189], v198
	ds_read_b128 v[208:211], v250
	ds_read_b128 v[212:215], v198 offset:2048
	ds_read_b128 v[216:219], v250 offset:2048
	ds_read_b128 v[220:223], v198 offset:4096
	ds_read_b128 v[224:227], v250 offset:4096
	ds_read_b128 v[228:231], v198 offset:6144
	ds_read_b128 v[232:235], v250 offset:6144
	global_load_lds_dwordx4 v[2:3], off
	v_lshl_add_u64 v[2:3], v[150:151], 0, s[66:67]
	s_add_i32 m0, s41, 0xe000
	s_nop 0
	global_load_lds_dwordx4 v[2:3], off
	s_waitcnt vmcnt(8)
	s_waitcnt lgkmcnt(0)
	s_setprio 2
	s_barrier
	v_mfma_f32_16x16x32_bf16 v[136:139], v[84:87], v[186:189], v[136:139]
	v_mfma_f32_16x16x32_bf16 v[136:139], v[96:99], v[208:211], v[136:139]
	v_mfma_f32_16x16x32_bf16 v[132:135], v[140:143], v[186:189], v[132:135]
	v_mfma_f32_16x16x32_bf16 v[132:135], v[144:147], v[208:211], v[132:135]
	v_mfma_f32_16x16x32_bf16 v[120:123], v[84:87], v[212:215], v[120:123]
	v_mfma_f32_16x16x32_bf16 v[120:123], v[96:99], v[216:219], v[120:123]
	v_mfma_f32_16x16x32_bf16 v[116:119], v[140:143], v[212:215], v[116:119]
	v_mfma_f32_16x16x32_bf16 v[116:119], v[144:147], v[216:219], v[116:119]
	v_mfma_f32_16x16x32_bf16 v[104:107], v[84:87], v[220:223], v[104:107]
	v_mfma_f32_16x16x32_bf16 v[104:107], v[96:99], v[224:227], v[104:107]
	v_mfma_f32_16x16x32_bf16 v[100:103], v[140:143], v[220:223], v[100:103]
	v_mfma_f32_16x16x32_bf16 v[100:103], v[144:147], v[224:227], v[100:103]
	v_mfma_f32_16x16x32_bf16 v[80:83], v[84:87], v[228:231], v[80:83]
	v_mfma_f32_16x16x32_bf16 v[80:83], v[96:99], v[232:235], v[80:83]
	v_mfma_f32_16x16x32_bf16 v[76:79], v[140:143], v[228:231], v[76:79]
	v_mfma_f32_16x16x32_bf16 v[76:79], v[144:147], v[232:235], v[76:79]
	s_setprio 0
	s_setprio 2
	v_mfma_f32_16x16x32_bf16 v[128:131], v[152:155], v[186:189], v[128:131]
	v_mfma_f32_16x16x32_bf16 v[128:131], v[156:159], v[208:211], v[128:131]
	v_mfma_f32_16x16x32_bf16 v[124:127], v[160:163], v[186:189], v[124:127]
	v_mfma_f32_16x16x32_bf16 v[124:127], v[182:185], v[208:211], v[124:127]
	v_mfma_f32_16x16x32_bf16 v[112:115], v[152:155], v[212:215], v[112:115]
	v_mfma_f32_16x16x32_bf16 v[112:115], v[156:159], v[216:219], v[112:115]
	v_mfma_f32_16x16x32_bf16 v[108:111], v[160:163], v[212:215], v[108:111]
	v_mfma_f32_16x16x32_bf16 v[108:111], v[182:185], v[216:219], v[108:111]
	v_mfma_f32_16x16x32_bf16 v[92:95], v[152:155], v[220:223], v[92:95]
	v_mfma_f32_16x16x32_bf16 v[92:95], v[156:159], v[224:227], v[92:95]
	v_mfma_f32_16x16x32_bf16 v[88:91], v[160:163], v[220:223], v[88:91]
	v_mfma_f32_16x16x32_bf16 v[88:91], v[182:185], v[224:227], v[88:91]
	v_mfma_f32_16x16x32_bf16 v[72:75], v[152:155], v[228:231], v[72:75]
	v_mfma_f32_16x16x32_bf16 v[72:75], v[156:159], v[232:235], v[72:75]
	v_mfma_f32_16x16x32_bf16 v[68:71], v[160:163], v[228:231], v[68:71]
	s_setprio 3
	s_barrier
	v_mfma_f32_16x16x32_bf16 v[68:71], v[182:185], v[232:235], v[68:71]
	s_setprio 0
	s_add_i32 s96, s88, s31
	s_mov_b32 m0, s96
	ds_read_b128 v[186:189], v198 offset:16384
	ds_read_b128 v[208:211], v250 offset:16384
	ds_read_b128 v[212:215], v198 offset:18432
	ds_read_b128 v[216:219], v250 offset:18432
	ds_read_b128 v[220:223], v198 offset:20480
	ds_read_b128 v[224:227], v250 offset:20480
	ds_read_b128 v[228:231], v198 offset:22528
	ds_read_b128 v[232:235], v250 offset:22528
	global_load_lds_dwordx4 v166, s[4:5]
	s_add_i32 m0, s96, 0x2000
	s_add_u32 s96, s4, 0x104000
	s_addc_u32 s97, s5, 0
	s_add_i32 s98, s89, s31
	global_load_lds_dwordx4 v170, s[4:5]
	s_mov_b32 m0, s98
	s_nop 0
	global_load_lds_dwordx4 v166, s[96:97]
	s_add_i32 m0, s98, 0x2000
	s_nop 0
	global_load_lds_dwordx4 v170, s[96:97]
	s_waitcnt vmcnt(6)
	s_waitcnt lgkmcnt(0)
	s_setprio 2
	s_barrier
; #define PG8_STAGE(bufoff, gbase, voff) do { _Pragma("unroll") for (int _i = 0; _i < 2; ++_i) \
;         __builtin_amdgcn_global_load_lds((const unsigned*)((const char*)(gbase) + (voff)[_i]), (LAS unsigned*)(lds + (bufoff) + ldsw + _i * 8192), 16, 0, 0); } while (0)
; #define PG8_LDA(dst, b, h) do { _Pragma("unroll") for (int m = 0; m < 4; ++m) _Pragma("unroll") for (int k = 0; k < 2; ++k) dst[m][k] = *(const LAS bf16x8*)(lds + PG8_SA(b, h) + aoff + m * 2048 + k * 1024); } while (0)
; #define PG8_LDB(dst, b, h) do { _Pragma("unroll") for (int n = 0; n < 2; ++n) _Pragma("unroll") for (int k = 0; k < 2; ++k) dst[n][k] = *(const LAS bf16x8*)(lds + PG8_SB(b, h) + boff + n * 2048 + k * 1024); } while (0)
; #define PG8_MMA(ai, bj, At, Bt) do { __builtin_amdgcn_s_setprio(3); _Pragma("unroll") for (int m = 0; m < 4; ++m) _Pragma("unroll") for (int n = 0; n < 2; ++n) _Pragma("unroll") for (int k = 0; k < 2; ++k) \
;         acc[ai][bj][m][n] = __builtin_amdgcn_mfma_f32_16x16x32_bf16(Bt[n][k], At[m][k], acc[ai][bj][m][n], 0, 0, 0); __builtin_amdgcn_s_setprio(0); } while (0)
; #define PG8_WAIT_V(n) asm volatile("s_waitcnt vmcnt(" #n ")" ::: "memory")
; #define PG8_WAIT_L(n) asm volatile("s_waitcnt lgkmcnt(" #n ")" ::: "memory")
; #define PG8_BAR __builtin_amdgcn_s_barrier()
; #define PG8_SCHED __builtin_amdgcn_sched_barrier(0)
; template <class Epi, class Sched, bool ALIGN_EPI = false, bool SP2 = false>
; __device__ __forceinline__ void gemm_phase(LAS unsigned char* lds, const Gemm g, const Sched& S, const Epi& E) {
;     ...
;             PG8_WAIT_V(8); PG8_WAIT_L(0); PG8_BAR; PG8_MMA(1, 0, At, B0); PG8_MMA(1, 1, At, B1); PG8_BAR; PG8_SCHED;
;             PG8_LDB(B0, 1, 0); PG8_LDB(B1, 1, 1); PG8_SCHED; PG8_LDA(At, 1, 0); PG8_STAGE(PG8_SA(0, 1), a2 + hsA, voffA);
	v_mfma_f32_16x16x32_bf16 v[64:67], v[84:87], v[186:189], v[64:67]
	v_mfma_f32_16x16x32_bf16 v[64:67], v[96:99], v[208:211], v[64:67]
	v_mfma_f32_16x16x32_bf16 v[60:63], v[140:143], v[186:189], v[60:63]
	v_mfma_f32_16x16x32_bf16 v[60:63], v[144:147], v[208:211], v[60:63]
	v_mfma_f32_16x16x32_bf16 v[48:51], v[84:87], v[212:215], v[48:51]
	v_mfma_f32_16x16x32_bf16 v[48:51], v[96:99], v[216:219], v[48:51]
	v_mfma_f32_16x16x32_bf16 v[44:47], v[140:143], v[212:215], v[44:47]
	v_mfma_f32_16x16x32_bf16 v[44:47], v[144:147], v[216:219], v[44:47]
	v_mfma_f32_16x16x32_bf16 v[32:35], v[84:87], v[220:223], v[32:35]
	v_mfma_f32_16x16x32_bf16 v[32:35], v[96:99], v[224:227], v[32:35]
	v_mfma_f32_16x16x32_bf16 v[28:31], v[140:143], v[220:223], v[28:31]
	v_mfma_f32_16x16x32_bf16 v[28:31], v[144:147], v[224:227], v[28:31]
	v_mfma_f32_16x16x32_bf16 v[16:19], v[84:87], v[228:231], v[16:19]
	v_mfma_f32_16x16x32_bf16 v[16:19], v[96:99], v[232:235], v[16:19]
	v_mfma_f32_16x16x32_bf16 v[12:15], v[140:143], v[228:231], v[12:15]
	v_mfma_f32_16x16x32_bf16 v[12:15], v[144:147], v[232:235], v[12:15]
	s_setprio 0
	s_setprio 2
	v_mfma_f32_16x16x32_bf16 v[56:59], v[152:155], v[186:189], v[56:59]
	v_mfma_f32_16x16x32_bf16 v[56:59], v[156:159], v[208:211], v[56:59]
	v_mfma_f32_16x16x32_bf16 v[52:55], v[160:163], v[186:189], v[52:55]
	v_mfma_f32_16x16x32_bf16 v[52:55], v[182:185], v[208:211], v[52:55]
	v_mfma_f32_16x16x32_bf16 v[40:43], v[152:155], v[212:215], v[40:43]
	v_mfma_f32_16x16x32_bf16 v[40:43], v[156:159], v[216:219], v[40:43]
	v_mfma_f32_16x16x32_bf16 v[36:39], v[160:163], v[212:215], v[36:39]
	v_mfma_f32_16x16x32_bf16 v[36:39], v[182:185], v[216:219], v[36:39]
	v_mfma_f32_16x16x32_bf16 v[24:27], v[152:155], v[220:223], v[24:27]
	v_mfma_f32_16x16x32_bf16 v[24:27], v[156:159], v[224:227], v[24:27]
	v_mfma_f32_16x16x32_bf16 v[20:23], v[160:163], v[220:223], v[20:23]
	v_mfma_f32_16x16x32_bf16 v[20:23], v[182:185], v[224:227], v[20:23]
	v_mfma_f32_16x16x32_bf16 v[8:11], v[152:155], v[228:231], v[8:11]
	v_mfma_f32_16x16x32_bf16 v[8:11], v[156:159], v[232:235], v[8:11]
	v_mfma_f32_16x16x32_bf16 v[2:5], v[160:163], v[228:231], v[4:7]
	s_setprio 3
	s_barrier
	v_mfma_f32_16x16x32_bf16 v[2:5], v[182:185], v[232:235], v[2:5]
	s_setprio 0
	s_add_i32 s96, 0, 0x18000
	v_add_u32_e32 v1, s96, v194
	v_xor_b32_e32 v253, 64, v1
	s_add_i32 s97, 0, 0x1c000
	ds_read_b128 v[84:87], v1
	ds_read_b128 v[96:99], v253
	ds_read_b128 v[140:143], v1 offset:2048
	ds_read_b128 v[144:147], v253 offset:2048
	v_add_u32_e32 v1, s97, v194
	v_xor_b32_e32 v253, 64, v1
	ds_read_b128 v[152:155], v1
	ds_read_b128 v[156:159], v253
	ds_read_b128 v[160:163], v1 offset:2048
	ds_read_b128 v[182:185], v253 offset:2048
	s_mov_b32 m0, s41
	s_nop 0
	global_load_lds_dwordx4 v164, s[8:9]
	s_mov_b32 m0, s68
	s_nop 0
	global_load_lds_dwordx4 v168, s[8:9]
	s_add_u32 s8, s8, 0x100000
	s_addc_u32 s9, s9, 0
	s_mov_b32 m0, s69
	ds_read_b128 v[186:189], v198 offset:32768
	ds_read_b128 v[208:211], v250 offset:32768
	ds_read_b128 v[212:215], v198 offset:34816
	ds_read_b128 v[216:219], v250 offset:34816
	ds_read_b128 v[220:223], v198 offset:36864
	ds_read_b128 v[224:227], v250 offset:36864
	ds_read_b128 v[228:231], v198 offset:38912
	ds_read_b128 v[232:235], v250 offset:38912
	global_load_lds_dwordx4 v164, s[8:9]
	s_mov_b32 m0, s70
	s_nop 0
	global_load_lds_dwordx4 v168, s[8:9]
	s_waitcnt vmcnt(8)
	s_waitcnt lgkmcnt(0)
	s_setprio 2
	s_barrier
; #define PG8_STAGE(bufoff, gbase, voff) do { _Pragma("unroll") for (int _i = 0; _i < 2; ++_i) \
;         __builtin_amdgcn_global_load_lds((const unsigned*)((const char*)(gbase) + (voff)[_i]), (LAS unsigned*)(lds + (bufoff) + ldsw + _i * 8192), 16, 0, 0); } while (0)
; #define PG8_LDA(dst, b, h) do { _Pragma("unroll") for (int m = 0; m < 4; ++m) _Pragma("unroll") for (int k = 0; k < 2; ++k) dst[m][k] = *(const LAS bf16x8*)(lds + PG8_SA(b, h) + aoff + m * 2048 + k * 1024); } while (0)
; #define PG8_MMA(ai, bj, At, Bt) do { __builtin_amdgcn_s_setprio(3); _Pragma("unroll") for (int m = 0; m < 4; ++m) _Pragma("unroll") for (int n = 0; n < 2; ++n) _Pragma("unroll") for (int k = 0; k < 2; ++k) \
;         acc[ai][bj][m][n] = __builtin_amdgcn_mfma_f32_16x16x32_bf16(Bt[n][k], At[m][k], acc[ai][bj][m][n], 0, 0, 0); __builtin_amdgcn_s_setprio(0); } while (0)
; #define PG8_WAIT_V(n) asm volatile("s_waitcnt vmcnt(" #n ")" ::: "memory")
; #define PG8_WAIT_L(n) asm volatile("s_waitcnt lgkmcnt(" #n ")" ::: "memory")
; #define PG8_BAR __builtin_amdgcn_s_barrier()
; #define PG8_SCHED __builtin_amdgcn_sched_barrier(0)
; template <class Epi, class Sched, bool ALIGN_EPI = false, bool SP2 = false>
; __device__ __forceinline__ void gemm_phase(LAS unsigned char* lds, const Gemm g, const Sched& S, const Epi& E) {
;     ...
;             PG8_WAIT_V(8); PG8_WAIT_L(0); PG8_BAR; PG8_MMA(0, 0, At, B0); PG8_MMA(0, 1, At, B1); PG8_BAR; PG8_SCHED;
;             PG8_LDA(At, 1, 1); PG8_STAGE(PG8_SB(1, 0), b3, voffB); PG8_STAGE(PG8_SB(1, 1), b3 + hsB, voffB); PG8_STAGE(PG8_SA(1, 0), a3, voffA);
;             PG8_WAIT_V(8); PG8_WAIT_L(0); PG8_BAR; PG8_MMA(1, 0, At, B0); PG8_MMA(1, 1, At, B1); PG8_BAR; PG8_SCHED;
	v_mfma_f32_16x16x32_bf16 v[136:139], v[84:87], v[186:189], v[136:139]
	v_mfma_f32_16x16x32_bf16 v[136:139], v[96:99], v[208:211], v[136:139]
	v_mfma_f32_16x16x32_bf16 v[132:135], v[140:143], v[186:189], v[132:135]
	v_mfma_f32_16x16x32_bf16 v[132:135], v[144:147], v[208:211], v[132:135]
	v_mfma_f32_16x16x32_bf16 v[120:123], v[84:87], v[212:215], v[120:123]
	v_mfma_f32_16x16x32_bf16 v[120:123], v[96:99], v[216:219], v[120:123]
	v_mfma_f32_16x16x32_bf16 v[116:119], v[140:143], v[212:215], v[116:119]
	v_mfma_f32_16x16x32_bf16 v[116:119], v[144:147], v[216:219], v[116:119]
	v_mfma_f32_16x16x32_bf16 v[104:107], v[84:87], v[220:223], v[104:107]
	v_mfma_f32_16x16x32_bf16 v[104:107], v[96:99], v[224:227], v[104:107]
	v_mfma_f32_16x16x32_bf16 v[100:103], v[140:143], v[220:223], v[100:103]
	v_mfma_f32_16x16x32_bf16 v[100:103], v[144:147], v[224:227], v[100:103]
	v_mfma_f32_16x16x32_bf16 v[80:83], v[84:87], v[228:231], v[80:83]
	v_mfma_f32_16x16x32_bf16 v[80:83], v[96:99], v[232:235], v[80:83]
	v_mfma_f32_16x16x32_bf16 v[76:79], v[140:143], v[228:231], v[76:79]
	v_mfma_f32_16x16x32_bf16 v[76:79], v[144:147], v[232:235], v[76:79]
	s_setprio 0
	s_setprio 2
	v_mfma_f32_16x16x32_bf16 v[128:131], v[152:155], v[186:189], v[128:131]
	v_mfma_f32_16x16x32_bf16 v[128:131], v[156:159], v[208:211], v[128:131]
	v_mfma_f32_16x16x32_bf16 v[124:127], v[160:163], v[186:189], v[124:127]
	v_mfma_f32_16x16x32_bf16 v[124:127], v[182:185], v[208:211], v[124:127]
	v_mfma_f32_16x16x32_bf16 v[112:115], v[152:155], v[212:215], v[112:115]
	v_mfma_f32_16x16x32_bf16 v[112:115], v[156:159], v[216:219], v[112:115]
	v_mfma_f32_16x16x32_bf16 v[108:111], v[160:163], v[212:215], v[108:111]
	v_mfma_f32_16x16x32_bf16 v[108:111], v[182:185], v[216:219], v[108:111]
	v_mfma_f32_16x16x32_bf16 v[92:95], v[152:155], v[220:223], v[92:95]
	v_mfma_f32_16x16x32_bf16 v[92:95], v[156:159], v[224:227], v[92:95]
	v_mfma_f32_16x16x32_bf16 v[88:91], v[160:163], v[220:223], v[88:91]
	v_mfma_f32_16x16x32_bf16 v[88:91], v[182:185], v[224:227], v[88:91]
	v_mfma_f32_16x16x32_bf16 v[72:75], v[152:155], v[228:231], v[72:75]
	v_mfma_f32_16x16x32_bf16 v[72:75], v[156:159], v[232:235], v[72:75]
	v_mfma_f32_16x16x32_bf16 v[68:71], v[160:163], v[228:231], v[68:71]
	s_setprio 3
	s_barrier
	v_mfma_f32_16x16x32_bf16 v[68:71], v[182:185], v[232:235], v[68:71]
	s_setprio 0
	s_add_i32 s8, s96, s31
	s_add_u32 s100, s4, s24
	s_addc_u32 s101, s5, s25
	s_mov_b32 m0, s8
	ds_read_b128 v[186:189], v198 offset:49152
	ds_read_b128 v[208:211], v250 offset:49152
	ds_read_b128 v[212:215], v198 offset:51200
	ds_read_b128 v[216:219], v250 offset:51200
	ds_read_b128 v[220:223], v198 offset:53248
	ds_read_b128 v[224:227], v250 offset:53248
	ds_read_b128 v[228:231], v198 offset:55296
	ds_read_b128 v[232:235], v250 offset:55296
	global_load_lds_dwordx4 v166, s[100:101]
	s_add_i32 m0, s8, 0x2000
	s_add_u32 s4, s4, 0x104080
	s_addc_u32 s5, s5, 0
	s_add_i32 s8, s97, s31
	global_load_lds_dwordx4 v170, s[100:101]
	s_mov_b32 m0, s8
	s_nop 0
	global_load_lds_dwordx4 v166, s[4:5]
	s_add_i32 m0, s8, 0x2000
	s_nop 0
	global_load_lds_dwordx4 v170, s[4:5]
	s_waitcnt vmcnt(6)
	s_waitcnt lgkmcnt(0)
	s_setprio 2
	s_barrier
	v_mfma_f32_16x16x32_bf16 v[64:67], v[84:87], v[186:189], v[64:67]
	v_mfma_f32_16x16x32_bf16 v[64:67], v[96:99], v[208:211], v[64:67]
	v_mfma_f32_16x16x32_bf16 v[60:63], v[140:143], v[186:189], v[60:63]
	v_mfma_f32_16x16x32_bf16 v[60:63], v[144:147], v[208:211], v[60:63]
	v_mfma_f32_16x16x32_bf16 v[48:51], v[84:87], v[212:215], v[48:51]
	v_mfma_f32_16x16x32_bf16 v[48:51], v[96:99], v[216:219], v[48:51]
	v_mfma_f32_16x16x32_bf16 v[44:47], v[140:143], v[212:215], v[44:47]
	v_mfma_f32_16x16x32_bf16 v[44:47], v[144:147], v[216:219], v[44:47]
	v_mfma_f32_16x16x32_bf16 v[32:35], v[84:87], v[220:223], v[32:35]
	v_mfma_f32_16x16x32_bf16 v[32:35], v[96:99], v[224:227], v[32:35]
	v_mfma_f32_16x16x32_bf16 v[28:31], v[140:143], v[220:223], v[28:31]
	v_mfma_f32_16x16x32_bf16 v[28:31], v[144:147], v[224:227], v[28:31]
	v_mfma_f32_16x16x32_bf16 v[16:19], v[84:87], v[228:231], v[16:19]
	v_mfma_f32_16x16x32_bf16 v[16:19], v[96:99], v[232:235], v[16:19]
	v_mfma_f32_16x16x32_bf16 v[12:15], v[140:143], v[228:231], v[12:15]
	v_mfma_f32_16x16x32_bf16 v[12:15], v[144:147], v[232:235], v[12:15]
	s_setprio 0
	s_setprio 2
	v_mfma_f32_16x16x32_bf16 v[56:59], v[152:155], v[186:189], v[56:59]
	v_mfma_f32_16x16x32_bf16 v[56:59], v[156:159], v[208:211], v[56:59]
	v_mfma_f32_16x16x32_bf16 v[52:55], v[160:163], v[186:189], v[52:55]
	v_mfma_f32_16x16x32_bf16 v[52:55], v[182:185], v[208:211], v[52:55]
	v_mfma_f32_16x16x32_bf16 v[40:43], v[152:155], v[212:215], v[40:43]
	v_mfma_f32_16x16x32_bf16 v[40:43], v[156:159], v[216:219], v[40:43]
	v_mfma_f32_16x16x32_bf16 v[36:39], v[160:163], v[212:215], v[36:39]
	v_mfma_f32_16x16x32_bf16 v[36:39], v[182:185], v[216:219], v[36:39]
	v_mfma_f32_16x16x32_bf16 v[24:27], v[152:155], v[220:223], v[24:27]
	v_mfma_f32_16x16x32_bf16 v[24:27], v[156:159], v[224:227], v[24:27]
	v_mfma_f32_16x16x32_bf16 v[20:23], v[160:163], v[220:223], v[20:23]
	v_mfma_f32_16x16x32_bf16 v[20:23], v[182:185], v[224:227], v[20:23]
	v_mfma_f32_16x16x32_bf16 v[6:9], v[152:155], v[228:231], v[8:11]
	v_mfma_f32_16x16x32_bf16 v[8:11], v[156:159], v[232:235], v[6:9]
	v_mfma_f32_16x16x32_bf16 v[2:5], v[160:163], v[228:231], v[2:5]
	s_setprio 3
	s_barrier
	v_mfma_f32_16x16x32_bf16 v[4:7], v[182:185], v[232:235], v[2:5]
	s_setprio 0
	s_add_i32 s95, s95, 2
	s_add_u32 s66, s66, 0x100
	s_addc_u32 s67, s67, 0
	s_cmp_gt_u32 s95, 61
	s_cbranch_scc1 .LBB0_237

; #define PG8_STAGE(bufoff, gbase, voff) do { _Pragma("unroll") for (int _i = 0; _i < 2; ++_i) \
;         __builtin_amdgcn_global_load_lds((const unsigned*)((const char*)(gbase) + (voff)[_i]), (LAS unsigned*)(lds + (bufoff) + ldsw + _i * 8192), 16, 0, 0); } while (0)
; #define PG8_LDA(dst, b, h) do { _Pragma("unroll") for (int m = 0; m < 4; ++m) _Pragma("unroll") for (int k = 0; k < 2; ++k) dst[m][k] = *(const LAS bf16x8*)(lds + PG8_SA(b, h) + aoff + m * 2048 + k * 1024); } while (0)
; #define PG8_LDB(dst, b, h) do { _Pragma("unroll") for (int n = 0; n < 2; ++n) _Pragma("unroll") for (int k = 0; k < 2; ++k) dst[n][k] = *(const LAS bf16x8*)(lds + PG8_SB(b, h) + boff + n * 2048 + k * 1024); } while (0)
; #define PG8_MMA(ai, bj, At, Bt) do { __builtin_amdgcn_s_setprio(3); _Pragma("unroll") for (int m = 0; m < 4; ++m) _Pragma("unroll") for (int n = 0; n < 2; ++n) _Pragma("unroll") for (int k = 0; k < 2; ++k) \
;         acc[ai][bj][m][n] = __builtin_amdgcn_mfma_f32_16x16x32_bf16(Bt[n][k], At[m][k], acc[ai][bj][m][n], 0, 0, 0); __builtin_amdgcn_s_setprio(0); } while (0)
; #define PG8_WAIT_V(n) asm volatile("s_waitcnt vmcnt(" #n ")" ::: "memory")
; #define PG8_BAR __builtin_amdgcn_s_barrier()
; template <class Epi, class Sched, bool ALIGN_EPI = false, bool SP2 = false>
; __device__ __forceinline__ void gemm_phase(LAS unsigned char* lds, const Gemm g, const Sched& S, const Epi& E) {
;     ...
;             const bool last = (t == nt - 2);
;             const char* a1 = cA + (size_t)(t + 1) * kstep;
;             const char* a2 = last ? nA : cA + (size_t)(t + 2) * kstep; const char* b2 = last ? nB : cB + (size_t)(t + 2) * kstep;
;             const char* a3 = a2 + kstep; const char* b3 = b2 + kstep;
;             if (last && has_next) S.a_ready(nxt);
;             if constexpr (Epi::MID) { if (t == nt / 2) E.mid(acc, cur, wr, wc, fr, fq); }
;             if constexpr (SP2) {
;             PG8_LDB(B0, 0, 0); PG8_LDB(B1, 0, 1); PG8_SCHED; PG8_LDA(At, 0, 0); PG8_STAGE(PG8_SA(1, 1), a1 + hsA, voffA);
;             PG8_WAIT_V(8); PG8_WAIT_L(0); PG8_BAR; PG8_MMA(0, 0, At, B0); PG8_MMA(0, 1, At, B1); PG8_BAR; PG8_SCHED;
;             PG8_LDA(At, 0, 1); PG8_STAGE(PG8_SB(0, 0), b2, voffB); PG8_STAGE(PG8_SB(0, 1), b2 + hsB, voffB); PG8_STAGE(PG8_SA(0, 0), a2, voffA);
;             PG8_WAIT_V(8); PG8_WAIT_L(0); PG8_BAR; PG8_MMA(1, 0, At, B0); PG8_MMA(1, 1, At, B1); PG8_BAR; PG8_SCHED;
.LBB0_309:
	ds_read_b128 v[112:115], v175
	ds_read_b128 v[132:135], v251
	ds_read_b128 v[136:139], v175 offset:2048
	ds_read_b128 v[140:143], v251 offset:2048
	ds_read_b128 v[144:147], v176
	ds_read_b128 v[148:151], v252
	ds_read_b128 v[184:187], v176 offset:2048
	ds_read_b128 v[188:191], v252 offset:2048
	s_add_u32 s24, s4, 0xffefc080
	s_addc_u32 s25, s5, -1
	s_cmp_eq_u32 s73, 60
	s_cselect_b32 s27, s11, s25
	s_cselect_b32 s26, s10, s24
	s_cselect_b32 s25, s21, s72
	s_cselect_b32 s24, s20, s71
	s_sub_u32 s100, s4, 0x104000
	s_subb_u32 s101, s5, 0
	s_mov_b32 m0, s42
	s_nop 0
	global_load_lds_dwordx4 v152, s[100:101]
	s_mov_b32 m0, s43
	s_nop 0
	global_load_lds_dwordx4 v156, s[100:101]
	s_add_i32 m0, s36, 0xc000
	ds_read_b128 v[192:195], v177
	ds_read_b128 v[196:199], v250
	ds_read_b128 v[206:209], v177 offset:2048
	ds_read_b128 v[210:213], v250 offset:2048
	ds_read_b128 v[214:217], v177 offset:4096
	ds_read_b128 v[218:221], v250 offset:4096
	ds_read_b128 v[222:225], v177 offset:6144
	ds_read_b128 v[226:229], v250 offset:6144
	global_load_lds_dwordx4 v164, s[4:5]
	s_add_i32 m0, s36, 0xe000
	s_nop 0
	global_load_lds_dwordx4 v166, s[4:5]
	s_waitcnt vmcnt(8)
	s_waitcnt lgkmcnt(0)
	s_setprio 2
	s_barrier
	v_mfma_f32_16x16x32_bf16 v[128:131], v[112:115], v[192:195], v[128:131]
	v_mfma_f32_16x16x32_bf16 v[128:131], v[132:135], v[196:199], v[128:131]
	v_mfma_f32_16x16x32_bf16 v[124:127], v[136:139], v[192:195], v[124:127]
	v_mfma_f32_16x16x32_bf16 v[124:127], v[140:143], v[196:199], v[124:127]
	v_mfma_f32_16x16x32_bf16 v[108:111], v[112:115], v[206:209], v[108:111]
	v_mfma_f32_16x16x32_bf16 v[108:111], v[132:135], v[210:213], v[108:111]
	v_mfma_f32_16x16x32_bf16 v[104:107], v[136:139], v[206:209], v[104:107]
	v_mfma_f32_16x16x32_bf16 v[104:107], v[140:143], v[210:213], v[104:107]
	v_mfma_f32_16x16x32_bf16 v[92:95], v[112:115], v[214:217], v[92:95]
	v_mfma_f32_16x16x32_bf16 v[92:95], v[132:135], v[218:221], v[92:95]
	v_mfma_f32_16x16x32_bf16 v[88:91], v[136:139], v[214:217], v[88:91]
	v_mfma_f32_16x16x32_bf16 v[88:91], v[140:143], v[218:221], v[88:91]
	v_mfma_f32_16x16x32_bf16 v[76:79], v[112:115], v[222:225], v[76:79]
	v_mfma_f32_16x16x32_bf16 v[76:79], v[132:135], v[226:229], v[76:79]
	v_mfma_f32_16x16x32_bf16 v[72:75], v[136:139], v[222:225], v[72:75]
	v_mfma_f32_16x16x32_bf16 v[72:75], v[140:143], v[226:229], v[72:75]
	s_setprio 0
	s_setprio 2
	v_mfma_f32_16x16x32_bf16 v[120:123], v[144:147], v[192:195], v[120:123]
	v_mfma_f32_16x16x32_bf16 v[120:123], v[148:151], v[196:199], v[120:123]
	v_mfma_f32_16x16x32_bf16 v[116:119], v[184:187], v[192:195], v[116:119]
	v_mfma_f32_16x16x32_bf16 v[116:119], v[188:191], v[196:199], v[116:119]
	v_mfma_f32_16x16x32_bf16 v[100:103], v[144:147], v[206:209], v[100:103]
	v_mfma_f32_16x16x32_bf16 v[100:103], v[148:151], v[210:213], v[100:103]
	v_mfma_f32_16x16x32_bf16 v[96:99], v[184:187], v[206:209], v[96:99]
	v_mfma_f32_16x16x32_bf16 v[96:99], v[188:191], v[210:213], v[96:99]
	v_mfma_f32_16x16x32_bf16 v[84:87], v[144:147], v[214:217], v[84:87]
	v_mfma_f32_16x16x32_bf16 v[84:87], v[148:151], v[218:221], v[84:87]
	v_mfma_f32_16x16x32_bf16 v[80:83], v[184:187], v[214:217], v[80:83]
	v_mfma_f32_16x16x32_bf16 v[80:83], v[188:191], v[218:221], v[80:83]
	v_mfma_f32_16x16x32_bf16 v[68:71], v[144:147], v[222:225], v[68:71]
	v_mfma_f32_16x16x32_bf16 v[68:71], v[148:151], v[226:229], v[68:71]
	v_mfma_f32_16x16x32_bf16 v[64:67], v[184:187], v[222:225], v[64:67]
	s_setprio 3
	s_barrier
	v_mfma_f32_16x16x32_bf16 v[64:67], v[188:191], v[226:229], v[64:67]
	s_setprio 0
	s_add_i32 s74, s45, s31
	s_mov_b32 m0, s74
	ds_read_b128 v[192:195], v177 offset:16384
	ds_read_b128 v[196:199], v250 offset:16384
	ds_read_b128 v[206:209], v177 offset:18432
	ds_read_b128 v[210:213], v250 offset:18432
	ds_read_b128 v[214:217], v177 offset:20480
	ds_read_b128 v[218:221], v250 offset:20480
	ds_read_b128 v[222:225], v177 offset:22528
	ds_read_b128 v[226:229], v250 offset:22528
	global_load_lds_dwordx4 v154, s[24:25]
	s_add_i32 m0, s74, 0x2000
	s_add_u32 s74, s24, 0x41000
	s_addc_u32 s75, s25, 0
	s_add_i32 s78, s46, s31
	global_load_lds_dwordx4 v158, s[24:25]
	s_mov_b32 m0, s78
	s_nop 0
	global_load_lds_dwordx4 v154, s[74:75]
	s_add_i32 m0, s78, 0x2000
	s_nop 0
	global_load_lds_dwordx4 v158, s[74:75]
	s_waitcnt vmcnt(6)
	s_waitcnt lgkmcnt(0)
	s_setprio 2
	s_barrier
	v_mfma_f32_16x16x32_bf16 v[60:63], v[112:115], v[192:195], v[60:63]
	v_mfma_f32_16x16x32_bf16 v[60:63], v[132:135], v[196:199], v[60:63]
	v_mfma_f32_16x16x32_bf16 v[56:59], v[136:139], v[192:195], v[56:59]
	v_mfma_f32_16x16x32_bf16 v[56:59], v[140:143], v[196:199], v[56:59]
	v_mfma_f32_16x16x32_bf16 v[44:47], v[112:115], v[206:209], v[44:47]
	v_mfma_f32_16x16x32_bf16 v[44:47], v[132:135], v[210:213], v[44:47]
	v_mfma_f32_16x16x32_bf16 v[40:43], v[136:139], v[206:209], v[40:43]
	v_mfma_f32_16x16x32_bf16 v[40:43], v[140:143], v[210:213], v[40:43]
	v_mfma_f32_16x16x32_bf16 v[28:31], v[112:115], v[214:217], v[28:31]
	v_mfma_f32_16x16x32_bf16 v[28:31], v[132:135], v[218:221], v[28:31]
	v_mfma_f32_16x16x32_bf16 v[24:27], v[136:139], v[214:217], v[24:27]
	v_mfma_f32_16x16x32_bf16 v[24:27], v[140:143], v[218:221], v[24:27]
	v_mfma_f32_16x16x32_bf16 v[12:15], v[112:115], v[222:225], v[12:15]
	v_mfma_f32_16x16x32_bf16 v[12:15], v[132:135], v[226:229], v[12:15]
	v_mfma_f32_16x16x32_bf16 v[8:11], v[136:139], v[222:225], v[8:11]
	v_mfma_f32_16x16x32_bf16 v[8:11], v[140:143], v[226:229], v[8:11]
	s_setprio 0
	s_setprio 2
	v_mfma_f32_16x16x32_bf16 v[52:55], v[144:147], v[192:195], v[52:55]
	v_mfma_f32_16x16x32_bf16 v[52:55], v[148:151], v[196:199], v[52:55]
	v_mfma_f32_16x16x32_bf16 v[48:51], v[184:187], v[192:195], v[48:51]
	v_mfma_f32_16x16x32_bf16 v[48:51], v[188:191], v[196:199], v[48:51]
	v_mfma_f32_16x16x32_bf16 v[36:39], v[144:147], v[206:209], v[36:39]
	v_mfma_f32_16x16x32_bf16 v[36:39], v[148:151], v[210:213], v[36:39]
	v_mfma_f32_16x16x32_bf16 v[32:35], v[184:187], v[206:209], v[32:35]
	v_mfma_f32_16x16x32_bf16 v[32:35], v[188:191], v[210:213], v[32:35]
	v_mfma_f32_16x16x32_bf16 v[20:23], v[144:147], v[214:217], v[20:23]
	v_mfma_f32_16x16x32_bf16 v[20:23], v[148:151], v[218:221], v[20:23]
	v_mfma_f32_16x16x32_bf16 v[16:19], v[184:187], v[214:217], v[16:19]
	v_mfma_f32_16x16x32_bf16 v[16:19], v[188:191], v[218:221], v[16:19]
	v_mfma_f32_16x16x32_bf16 v[4:7], v[144:147], v[222:225], v[4:7]
	v_mfma_f32_16x16x32_bf16 v[4:7], v[148:151], v[226:229], v[4:7]
	v_mfma_f32_16x16x32_bf16 v[0:3], v[184:187], v[222:225], v[0:3]
	s_setprio 3
	s_barrier
; #define PG8_STAGE(bufoff, gbase, voff) do { _Pragma("unroll") for (int _i = 0; _i < 2; ++_i) \
;         __builtin_amdgcn_global_load_lds((const unsigned*)((const char*)(gbase) + (voff)[_i]), (LAS unsigned*)(lds + (bufoff) + ldsw + _i * 8192), 16, 0, 0); } while (0)
; #define PG8_LDA(dst, b, h) do { _Pragma("unroll") for (int m = 0; m < 4; ++m) _Pragma("unroll") for (int k = 0; k < 2; ++k) dst[m][k] = *(const LAS bf16x8*)(lds + PG8_SA(b, h) + aoff + m * 2048 + k * 1024); } while (0)
; #define PG8_LDB(dst, b, h) do { _Pragma("unroll") for (int n = 0; n < 2; ++n) _Pragma("unroll") for (int k = 0; k < 2; ++k) dst[n][k] = *(const LAS bf16x8*)(lds + PG8_SB(b, h) + boff + n * 2048 + k * 1024); } while (0)
; #define PG8_MMA(ai, bj, At, Bt) do { __builtin_amdgcn_s_setprio(3); _Pragma("unroll") for (int m = 0; m < 4; ++m) _Pragma("unroll") for (int n = 0; n < 2; ++n) _Pragma("unroll") for (int k = 0; k < 2; ++k) \
;         acc[ai][bj][m][n] = __builtin_amdgcn_mfma_f32_16x16x32_bf16(Bt[n][k], At[m][k], acc[ai][bj][m][n], 0, 0, 0); __builtin_amdgcn_s_setprio(0); } while (0)
; #define PG8_WAIT_V(n) asm volatile("s_waitcnt vmcnt(" #n ")" ::: "memory")
; #define PG8_WAIT_L(n) asm volatile("s_waitcnt lgkmcnt(" #n ")" ::: "memory")
; #define PG8_BAR __builtin_amdgcn_s_barrier()
; #define PG8_SCHED __builtin_amdgcn_sched_barrier(0)
; template <class Epi, class Sched, bool ALIGN_EPI = false, bool SP2 = false>
; __device__ __forceinline__ void gemm_phase(LAS unsigned char* lds, const Gemm g, const Sched& S, const Epi& E) {
;     ...
;             PG8_WAIT_V(8); PG8_WAIT_L(0); PG8_BAR; PG8_MMA(1, 0, At, B0); PG8_MMA(1, 1, At, B1); PG8_BAR; PG8_SCHED;
;             PG8_LDB(B0, 1, 0); PG8_LDB(B1, 1, 1); PG8_SCHED; PG8_LDA(At, 1, 0); PG8_STAGE(PG8_SA(0, 1), a2 + hsA, voffA);
;             PG8_WAIT_V(8); PG8_WAIT_L(0); PG8_BAR; PG8_MMA(0, 0, At, B0); PG8_MMA(0, 1, At, B1); PG8_BAR; PG8_SCHED;
;             PG8_LDA(At, 1, 1); PG8_STAGE(PG8_SB(1, 0), b3, voffB); PG8_STAGE(PG8_SB(1, 1), b3 + hsB, voffB); PG8_STAGE(PG8_SA(1, 0), a3, voffA);
;             PG8_WAIT_V(8); PG8_WAIT_L(0); PG8_BAR; PG8_MMA(1, 0, At, B0); PG8_MMA(1, 1, At, B1); PG8_BAR; PG8_SCHED;
;     ...
;         if constexpr (ALIGN_EPI) { if (wr == 0) PG8_BAR; }
	v_mfma_f32_16x16x32_bf16 v[0:3], v[188:191], v[226:229], v[0:3]
	s_setprio 0
	s_add_i32 s74, 0, 0x18000
	s_add_i32 s75, 0, 0x1c000
	v_add_u32_e32 v140, s74, v173
	v_xor_b32_e32 v253, 64, v140
	v_add_u32_e32 v188, s75, v173
	v_xor_b32_e32 v254, 64, v188
	ds_read_b128 v[112:115], v140
	ds_read_b128 v[132:135], v253
	ds_read_b128 v[136:139], v140 offset:2048
	ds_read_b128 v[140:143], v253 offset:2048
	ds_read_b128 v[144:147], v188
	ds_read_b128 v[148:151], v254
	ds_read_b128 v[184:187], v188 offset:2048
	ds_read_b128 v[188:191], v254 offset:2048
	s_mov_b32 m0, s36
	s_nop 0
	global_load_lds_dwordx4 v152, s[26:27]
	s_mov_b32 m0, s37
	s_nop 0
	global_load_lds_dwordx4 v156, s[26:27]
	s_add_u32 s26, s26, 0x104000
	s_addc_u32 s27, s27, 0
	s_mov_b32 m0, s38
	ds_read_b128 v[192:195], v177 offset:32768
	ds_read_b128 v[196:199], v250 offset:32768
	ds_read_b128 v[206:209], v177 offset:34816
	ds_read_b128 v[210:213], v250 offset:34816
	ds_read_b128 v[214:217], v177 offset:36864
	ds_read_b128 v[218:221], v250 offset:36864
	ds_read_b128 v[222:225], v177 offset:38912
	ds_read_b128 v[226:229], v250 offset:38912
	global_load_lds_dwordx4 v152, s[26:27]
	s_mov_b32 m0, s39
	s_nop 0
	global_load_lds_dwordx4 v156, s[26:27]
	s_waitcnt vmcnt(8)
	s_waitcnt lgkmcnt(0)
	s_setprio 2
	s_barrier
	v_mfma_f32_16x16x32_bf16 v[128:131], v[112:115], v[192:195], v[128:131]
	v_mfma_f32_16x16x32_bf16 v[128:131], v[132:135], v[196:199], v[128:131]
	v_mfma_f32_16x16x32_bf16 v[124:127], v[136:139], v[192:195], v[124:127]
	v_mfma_f32_16x16x32_bf16 v[124:127], v[140:143], v[196:199], v[124:127]
	v_mfma_f32_16x16x32_bf16 v[108:111], v[112:115], v[206:209], v[108:111]
	v_mfma_f32_16x16x32_bf16 v[108:111], v[132:135], v[210:213], v[108:111]
	v_mfma_f32_16x16x32_bf16 v[104:107], v[136:139], v[206:209], v[104:107]
	v_mfma_f32_16x16x32_bf16 v[104:107], v[140:143], v[210:213], v[104:107]
	v_mfma_f32_16x16x32_bf16 v[92:95], v[112:115], v[214:217], v[92:95]
	v_mfma_f32_16x16x32_bf16 v[92:95], v[132:135], v[218:221], v[92:95]
	v_mfma_f32_16x16x32_bf16 v[88:91], v[136:139], v[214:217], v[88:91]
	v_mfma_f32_16x16x32_bf16 v[88:91], v[140:143], v[218:221], v[88:91]
	v_mfma_f32_16x16x32_bf16 v[76:79], v[112:115], v[222:225], v[76:79]
	v_mfma_f32_16x16x32_bf16 v[76:79], v[132:135], v[226:229], v[76:79]
	v_mfma_f32_16x16x32_bf16 v[72:75], v[136:139], v[222:225], v[72:75]
	v_mfma_f32_16x16x32_bf16 v[72:75], v[140:143], v[226:229], v[72:75]
	s_setprio 0
	s_setprio 2
	v_mfma_f32_16x16x32_bf16 v[120:123], v[144:147], v[192:195], v[120:123]
	v_mfma_f32_16x16x32_bf16 v[120:123], v[148:151], v[196:199], v[120:123]
	v_mfma_f32_16x16x32_bf16 v[116:119], v[184:187], v[192:195], v[116:119]
	v_mfma_f32_16x16x32_bf16 v[116:119], v[188:191], v[196:199], v[116:119]
	v_mfma_f32_16x16x32_bf16 v[100:103], v[144:147], v[206:209], v[100:103]
	v_mfma_f32_16x16x32_bf16 v[100:103], v[148:151], v[210:213], v[100:103]
	v_mfma_f32_16x16x32_bf16 v[96:99], v[184:187], v[206:209], v[96:99]
	v_mfma_f32_16x16x32_bf16 v[96:99], v[188:191], v[210:213], v[96:99]
	v_mfma_f32_16x16x32_bf16 v[84:87], v[144:147], v[214:217], v[84:87]
	v_mfma_f32_16x16x32_bf16 v[84:87], v[148:151], v[218:221], v[84:87]
	v_mfma_f32_16x16x32_bf16 v[80:83], v[184:187], v[214:217], v[80:83]
	v_mfma_f32_16x16x32_bf16 v[80:83], v[188:191], v[218:221], v[80:83]
	v_mfma_f32_16x16x32_bf16 v[68:71], v[144:147], v[222:225], v[68:71]
	v_mfma_f32_16x16x32_bf16 v[68:71], v[148:151], v[226:229], v[68:71]
	v_mfma_f32_16x16x32_bf16 v[64:67], v[184:187], v[222:225], v[64:67]
	s_setprio 3
	s_barrier
	v_mfma_f32_16x16x32_bf16 v[64:67], v[188:191], v[226:229], v[64:67]
	s_setprio 0
	s_add_i32 s26, s74, s31
	s_add_u32 s100, s24, s14
	s_addc_u32 s101, s25, s15
	s_mov_b32 m0, s26
	ds_read_b128 v[192:195], v177 offset:49152
	ds_read_b128 v[196:199], v250 offset:49152
	ds_read_b128 v[206:209], v177 offset:51200
	ds_read_b128 v[210:213], v250 offset:51200
	ds_read_b128 v[214:217], v177 offset:53248
	ds_read_b128 v[218:221], v250 offset:53248
	ds_read_b128 v[222:225], v177 offset:55296
	ds_read_b128 v[226:229], v250 offset:55296
	global_load_lds_dwordx4 v154, s[100:101]
	s_add_i32 m0, s26, 0x2000
	s_add_u32 s24, s24, 0x41080
	s_addc_u32 s25, s25, 0
	s_add_i32 s26, s75, s31
	global_load_lds_dwordx4 v158, s[100:101]
	s_mov_b32 m0, s26
	s_nop 0
	global_load_lds_dwordx4 v154, s[24:25]
	s_add_i32 m0, s26, 0x2000
	s_nop 0
	global_load_lds_dwordx4 v158, s[24:25]
	s_waitcnt vmcnt(6)
	s_waitcnt lgkmcnt(0)
	s_setprio 2
	s_barrier
	v_mfma_f32_16x16x32_bf16 v[60:63], v[112:115], v[192:195], v[60:63]
	v_mfma_f32_16x16x32_bf16 v[60:63], v[132:135], v[196:199], v[60:63]
	v_mfma_f32_16x16x32_bf16 v[56:59], v[136:139], v[192:195], v[56:59]
	v_mfma_f32_16x16x32_bf16 v[56:59], v[140:143], v[196:199], v[56:59]
	v_mfma_f32_16x16x32_bf16 v[44:47], v[112:115], v[206:209], v[44:47]
	v_mfma_f32_16x16x32_bf16 v[44:47], v[132:135], v[210:213], v[44:47]
	v_mfma_f32_16x16x32_bf16 v[40:43], v[136:139], v[206:209], v[40:43]
	v_mfma_f32_16x16x32_bf16 v[40:43], v[140:143], v[210:213], v[40:43]
	v_mfma_f32_16x16x32_bf16 v[28:31], v[112:115], v[214:217], v[28:31]
	v_mfma_f32_16x16x32_bf16 v[28:31], v[132:135], v[218:221], v[28:31]
	v_mfma_f32_16x16x32_bf16 v[24:27], v[136:139], v[214:217], v[24:27]
	v_mfma_f32_16x16x32_bf16 v[24:27], v[140:143], v[218:221], v[24:27]
	v_mfma_f32_16x16x32_bf16 v[12:15], v[112:115], v[222:225], v[12:15]
	v_mfma_f32_16x16x32_bf16 v[12:15], v[132:135], v[226:229], v[12:15]
	v_mfma_f32_16x16x32_bf16 v[8:11], v[136:139], v[222:225], v[8:11]
	v_mfma_f32_16x16x32_bf16 v[8:11], v[140:143], v[226:229], v[8:11]
	s_setprio 0
	s_setprio 2
	v_mfma_f32_16x16x32_bf16 v[52:55], v[144:147], v[192:195], v[52:55]
	v_mfma_f32_16x16x32_bf16 v[52:55], v[148:151], v[196:199], v[52:55]
	v_mfma_f32_16x16x32_bf16 v[48:51], v[184:187], v[192:195], v[48:51]
	v_mfma_f32_16x16x32_bf16 v[48:51], v[188:191], v[196:199], v[48:51]
	v_mfma_f32_16x16x32_bf16 v[36:39], v[144:147], v[206:209], v[36:39]
	v_mfma_f32_16x16x32_bf16 v[36:39], v[148:151], v[210:213], v[36:39]
	v_mfma_f32_16x16x32_bf16 v[32:35], v[184:187], v[206:209], v[32:35]
	v_mfma_f32_16x16x32_bf16 v[32:35], v[188:191], v[210:213], v[32:35]
	v_mfma_f32_16x16x32_bf16 v[20:23], v[144:147], v[214:217], v[20:23]
	v_mfma_f32_16x16x32_bf16 v[20:23], v[148:151], v[218:221], v[20:23]
	v_mfma_f32_16x16x32_bf16 v[16:19], v[184:187], v[214:217], v[16:19]
	v_mfma_f32_16x16x32_bf16 v[16:19], v[188:191], v[218:221], v[16:19]
	v_mfma_f32_16x16x32_bf16 v[4:7], v[144:147], v[222:225], v[4:7]
	v_mfma_f32_16x16x32_bf16 v[4:7], v[148:151], v[226:229], v[4:7]
	v_mfma_f32_16x16x32_bf16 v[0:3], v[184:187], v[222:225], v[0:3]
	s_setprio 3
	s_barrier
	v_mfma_f32_16x16x32_bf16 v[0:3], v[188:191], v[226:229], v[0:3]
	s_setprio 0
	s_add_i32 s73, s73, 2
	s_add_u32 s4, s4, 0x100
	s_addc_u32 s5, s5, 0
	s_add_u32 s71, s71, 0x100
	s_addc_u32 s72, s72, 0
	s_cmp_gt_u32 s73, 61
	s_cbranch_scc0 .LBB0_309
	s_and_b64 vcc, exec, s[16:17]
	s_cbranch_vccz .LBB0_312
	s_barrier

; #define PG8_STAGE(bufoff, gbase, voff) do { _Pragma("unroll") for (int _i = 0; _i < 2; ++_i) \
;         __builtin_amdgcn_global_load_lds((const unsigned*)((const char*)(gbase) + (voff)[_i]), (LAS unsigned*)(lds + (bufoff) + ldsw + _i * 8192), 16, 0, 0); } while (0)
; #define PG8_LDA(dst, b, h) do { _Pragma("unroll") for (int m = 0; m < 4; ++m) _Pragma("unroll") for (int k = 0; k < 2; ++k) dst[m][k] = *(const LAS bf16x8*)(lds + PG8_SA(b, h) + aoff + m * 2048 + k * 1024); } while (0)
; #define PG8_LDB(dst, b, h) do { _Pragma("unroll") for (int n = 0; n < 2; ++n) _Pragma("unroll") for (int k = 0; k < 2; ++k) dst[n][k] = *(const LAS bf16x8*)(lds + PG8_SB(b, h) + boff + n * 2048 + k * 1024); } while (0)
; #define PG8_MMA(ai, bj, At, Bt) do { __builtin_amdgcn_s_setprio(3); _Pragma("unroll") for (int m = 0; m < 4; ++m) _Pragma("unroll") for (int n = 0; n < 2; ++n) _Pragma("unroll") for (int k = 0; k < 2; ++k) \
;         acc[ai][bj][m][n] = __builtin_amdgcn_mfma_f32_16x16x32_bf16(Bt[n][k], At[m][k], acc[ai][bj][m][n], 0, 0, 0); __builtin_amdgcn_s_setprio(0); } while (0)
; #define PG8_WAIT_V(n) asm volatile("s_waitcnt vmcnt(" #n ")" ::: "memory")
; #define PG8_BAR __builtin_amdgcn_s_barrier()
; template <class Epi, class Sched, bool ALIGN_EPI = false, bool SP2 = false>
; __device__ __forceinline__ void gemm_phase(LAS unsigned char* lds, const Gemm g, const Sched& S, const Epi& E) {
;     ...
;             const bool last = (t == nt - 2);
;             const char* a1 = cA + (size_t)(t + 1) * kstep;
;             const char* a2 = last ? nA : cA + (size_t)(t + 2) * kstep; const char* b2 = last ? nB : cB + (size_t)(t + 2) * kstep;
;             const char* a3 = a2 + kstep; const char* b3 = b2 + kstep;
;             if (last && has_next) S.a_ready(nxt);
;             if constexpr (Epi::MID) { if (t == nt / 2) E.mid(acc, cur, wr, wc, fr, fq); }
;             if constexpr (SP2) {
;             PG8_LDB(B0, 0, 0); PG8_LDB(B1, 0, 1); PG8_SCHED; PG8_LDA(At, 0, 0); PG8_STAGE(PG8_SA(1, 1), a1 + hsA, voffA);
;             PG8_WAIT_V(8); PG8_WAIT_L(0); PG8_BAR; PG8_MMA(0, 0, At, B0); PG8_MMA(0, 1, At, B1); PG8_BAR; PG8_SCHED;
;             PG8_LDA(At, 0, 1); PG8_STAGE(PG8_SB(0, 0), b2, voffB); PG8_STAGE(PG8_SB(0, 1), b2 + hsB, voffB); PG8_STAGE(PG8_SA(0, 0), a2, voffA);
;             PG8_WAIT_V(8); PG8_WAIT_L(0); PG8_BAR; PG8_MMA(1, 0, At, B0); PG8_MMA(1, 1, At, B1); PG8_BAR; PG8_SCHED;
.LBB0_350:
	ds_read_b128 v[140:143], v149
	ds_read_b128 v[156:159], v251
	ds_read_b128 v[160:163], v149 offset:2048
	ds_read_b128 v[164:167], v251 offset:2048
	ds_read_b128 v[168:171], v150
	ds_read_b128 v[172:175], v252
	ds_read_b128 v[176:179], v150 offset:2048
	ds_read_b128 v[180:183], v252 offset:2048
	s_add_u32 s16, s14, 0xffbfc080
	s_addc_u32 s17, s15, -1
	s_cmpk_eq_i32 s50, 0xfc
	s_cselect_b32 s21, s5, s17
	s_cselect_b32 s20, s4, s16
	s_cselect_b32 s17, s13, s49
	s_cselect_b32 s16, s12, s48
	s_sub_u32 s100, s14, 0x404000
	s_subb_u32 s101, s15, 0
	s_mov_b32 m0, s33
	s_nop 0
	global_load_lds_dwordx4 v128, s[100:101]
	s_mov_b32 m0, s38
	s_nop 0
	global_load_lds_dwordx4 v130, s[100:101]
	s_add_i32 m0, s26, 0xc000
	ds_read_b128 v[184:187], v151
	ds_read_b128 v[188:191], v250
	ds_read_b128 v[192:195], v151 offset:2048
	ds_read_b128 v[196:199], v250 offset:2048
	ds_read_b128 v[200:203], v151 offset:4096
	ds_read_b128 v[204:207], v250 offset:4096
	ds_read_b128 v[208:211], v151 offset:6144
	ds_read_b128 v[212:215], v250 offset:6144
	global_load_lds_dwordx4 v132, s[14:15]
	s_add_i32 m0, s26, 0xe000
	s_nop 0
	global_load_lds_dwordx4 v134, s[14:15]
	s_waitcnt vmcnt(8)
	s_waitcnt lgkmcnt(0)
	s_setprio 2
	s_barrier
	v_mfma_f32_16x16x32_bf16 v[124:127], v[140:143], v[184:187], v[124:127]
	v_mfma_f32_16x16x32_bf16 v[124:127], v[156:159], v[188:191], v[124:127]
	v_mfma_f32_16x16x32_bf16 v[120:123], v[160:163], v[184:187], v[120:123]
	v_mfma_f32_16x16x32_bf16 v[120:123], v[164:167], v[188:191], v[120:123]
	v_mfma_f32_16x16x32_bf16 v[108:111], v[140:143], v[192:195], v[108:111]
	v_mfma_f32_16x16x32_bf16 v[108:111], v[156:159], v[196:199], v[108:111]
	v_mfma_f32_16x16x32_bf16 v[104:107], v[160:163], v[192:195], v[104:107]
	v_mfma_f32_16x16x32_bf16 v[104:107], v[164:167], v[196:199], v[104:107]
	v_mfma_f32_16x16x32_bf16 v[92:95], v[140:143], v[200:203], v[92:95]
	v_mfma_f32_16x16x32_bf16 v[92:95], v[156:159], v[204:207], v[92:95]
	v_mfma_f32_16x16x32_bf16 v[88:91], v[160:163], v[200:203], v[88:91]
	v_mfma_f32_16x16x32_bf16 v[88:91], v[164:167], v[204:207], v[88:91]
	v_mfma_f32_16x16x32_bf16 v[76:79], v[140:143], v[208:211], v[76:79]
	v_mfma_f32_16x16x32_bf16 v[76:79], v[156:159], v[212:215], v[76:79]
	v_mfma_f32_16x16x32_bf16 v[72:75], v[160:163], v[208:211], v[72:75]
	v_mfma_f32_16x16x32_bf16 v[72:75], v[164:167], v[212:215], v[72:75]
	s_setprio 0
	s_setprio 2
	v_mfma_f32_16x16x32_bf16 v[116:119], v[168:171], v[184:187], v[116:119]
	v_mfma_f32_16x16x32_bf16 v[116:119], v[172:175], v[188:191], v[116:119]
	v_mfma_f32_16x16x32_bf16 v[112:115], v[176:179], v[184:187], v[112:115]
	v_mfma_f32_16x16x32_bf16 v[112:115], v[180:183], v[188:191], v[112:115]
	v_mfma_f32_16x16x32_bf16 v[100:103], v[168:171], v[192:195], v[100:103]
	v_mfma_f32_16x16x32_bf16 v[100:103], v[172:175], v[196:199], v[100:103]
	v_mfma_f32_16x16x32_bf16 v[96:99], v[176:179], v[192:195], v[96:99]
	v_mfma_f32_16x16x32_bf16 v[96:99], v[180:183], v[196:199], v[96:99]
	v_mfma_f32_16x16x32_bf16 v[84:87], v[168:171], v[200:203], v[84:87]
	v_mfma_f32_16x16x32_bf16 v[84:87], v[172:175], v[204:207], v[84:87]
	v_mfma_f32_16x16x32_bf16 v[80:83], v[176:179], v[200:203], v[80:83]
	v_mfma_f32_16x16x32_bf16 v[80:83], v[180:183], v[204:207], v[80:83]
	v_mfma_f32_16x16x32_bf16 v[68:71], v[168:171], v[208:211], v[68:71]
	v_mfma_f32_16x16x32_bf16 v[68:71], v[172:175], v[212:215], v[68:71]
	s_setprio 3
	s_barrier
	v_mfma_f32_16x16x32_bf16 v[64:67], v[176:179], v[208:211], v[64:67]
	v_mfma_f32_16x16x32_bf16 v[64:67], v[180:183], v[212:215], v[64:67]
	s_setprio 0
	s_add_i32 s51, s41, s25
	s_mov_b32 m0, s51
	ds_read_b128 v[184:187], v151 offset:16384
	ds_read_b128 v[188:191], v250 offset:16384
	ds_read_b128 v[192:195], v151 offset:18432
	ds_read_b128 v[196:199], v250 offset:18432
	ds_read_b128 v[200:203], v151 offset:20480
	ds_read_b128 v[204:207], v250 offset:20480
	ds_read_b128 v[208:211], v151 offset:22528
	ds_read_b128 v[212:215], v250 offset:22528
	global_load_lds_dwordx4 v128, s[16:17]
	s_add_i32 m0, s51, 0x2000
	s_add_u32 s52, s16, 0x404000
	s_addc_u32 s53, s17, 0
	s_add_i32 s51, s42, s25
	global_load_lds_dwordx4 v130, s[16:17]
	s_mov_b32 m0, s51
	s_nop 0
	global_load_lds_dwordx4 v128, s[52:53]
	s_add_i32 m0, s51, 0x2000
	s_nop 0
	global_load_lds_dwordx4 v130, s[52:53]
	s_waitcnt vmcnt(6)
	s_waitcnt lgkmcnt(0)
	s_setprio 2
	s_barrier
	v_mfma_f32_16x16x32_bf16 v[60:63], v[140:143], v[184:187], v[60:63]
	v_mfma_f32_16x16x32_bf16 v[60:63], v[156:159], v[188:191], v[60:63]
	v_mfma_f32_16x16x32_bf16 v[56:59], v[160:163], v[184:187], v[56:59]
	v_mfma_f32_16x16x32_bf16 v[56:59], v[164:167], v[188:191], v[56:59]
	v_mfma_f32_16x16x32_bf16 v[44:47], v[140:143], v[192:195], v[44:47]
	v_mfma_f32_16x16x32_bf16 v[44:47], v[156:159], v[196:199], v[44:47]
	v_mfma_f32_16x16x32_bf16 v[40:43], v[160:163], v[192:195], v[40:43]
	v_mfma_f32_16x16x32_bf16 v[40:43], v[164:167], v[196:199], v[40:43]
	v_mfma_f32_16x16x32_bf16 v[28:31], v[140:143], v[200:203], v[28:31]
	v_mfma_f32_16x16x32_bf16 v[28:31], v[156:159], v[204:207], v[28:31]
	v_mfma_f32_16x16x32_bf16 v[24:27], v[160:163], v[200:203], v[24:27]
	v_mfma_f32_16x16x32_bf16 v[24:27], v[164:167], v[204:207], v[24:27]
	v_mfma_f32_16x16x32_bf16 v[12:15], v[140:143], v[208:211], v[12:15]
	v_mfma_f32_16x16x32_bf16 v[12:15], v[156:159], v[212:215], v[12:15]
	v_mfma_f32_16x16x32_bf16 v[8:11], v[160:163], v[208:211], v[8:11]
	v_mfma_f32_16x16x32_bf16 v[8:11], v[164:167], v[212:215], v[8:11]
	s_setprio 0
	s_setprio 2
	v_mfma_f32_16x16x32_bf16 v[52:55], v[168:171], v[184:187], v[52:55]
	v_mfma_f32_16x16x32_bf16 v[52:55], v[172:175], v[188:191], v[52:55]
	v_mfma_f32_16x16x32_bf16 v[48:51], v[176:179], v[184:187], v[48:51]
	v_mfma_f32_16x16x32_bf16 v[48:51], v[180:183], v[188:191], v[48:51]
	v_mfma_f32_16x16x32_bf16 v[36:39], v[168:171], v[192:195], v[36:39]
	v_mfma_f32_16x16x32_bf16 v[36:39], v[172:175], v[196:199], v[36:39]
	v_mfma_f32_16x16x32_bf16 v[32:35], v[176:179], v[192:195], v[32:35]
	v_mfma_f32_16x16x32_bf16 v[32:35], v[180:183], v[196:199], v[32:35]
	v_mfma_f32_16x16x32_bf16 v[20:23], v[168:171], v[200:203], v[20:23]
	v_mfma_f32_16x16x32_bf16 v[20:23], v[172:175], v[204:207], v[20:23]
	v_mfma_f32_16x16x32_bf16 v[16:19], v[176:179], v[200:203], v[16:19]
	v_mfma_f32_16x16x32_bf16 v[16:19], v[180:183], v[204:207], v[16:19]
	v_mfma_f32_16x16x32_bf16 v[4:7], v[168:171], v[208:211], v[4:7]
	v_mfma_f32_16x16x32_bf16 v[4:7], v[172:175], v[212:215], v[4:7]
	s_setprio 3
	s_barrier
; #define PG8_STAGE(bufoff, gbase, voff) do { _Pragma("unroll") for (int _i = 0; _i < 2; ++_i) \
;         __builtin_amdgcn_global_load_lds((const unsigned*)((const char*)(gbase) + (voff)[_i]), (LAS unsigned*)(lds + (bufoff) + ldsw + _i * 8192), 16, 0, 0); } while (0)
; #define PG8_LDA(dst, b, h) do { _Pragma("unroll") for (int m = 0; m < 4; ++m) _Pragma("unroll") for (int k = 0; k < 2; ++k) dst[m][k] = *(const LAS bf16x8*)(lds + PG8_SA(b, h) + aoff + m * 2048 + k * 1024); } while (0)
; #define PG8_LDB(dst, b, h) do { _Pragma("unroll") for (int n = 0; n < 2; ++n) _Pragma("unroll") for (int k = 0; k < 2; ++k) dst[n][k] = *(const LAS bf16x8*)(lds + PG8_SB(b, h) + boff + n * 2048 + k * 1024); } while (0)
; #define PG8_MMA(ai, bj, At, Bt) do { __builtin_amdgcn_s_setprio(3); _Pragma("unroll") for (int m = 0; m < 4; ++m) _Pragma("unroll") for (int n = 0; n < 2; ++n) _Pragma("unroll") for (int k = 0; k < 2; ++k) \
;         acc[ai][bj][m][n] = __builtin_amdgcn_mfma_f32_16x16x32_bf16(Bt[n][k], At[m][k], acc[ai][bj][m][n], 0, 0, 0); __builtin_amdgcn_s_setprio(0); } while (0)
; #define PG8_WAIT_V(n) asm volatile("s_waitcnt vmcnt(" #n ")" ::: "memory")
; #define PG8_WAIT_L(n) asm volatile("s_waitcnt lgkmcnt(" #n ")" ::: "memory")
; #define PG8_BAR __builtin_amdgcn_s_barrier()
; #define PG8_SCHED __builtin_amdgcn_sched_barrier(0)
; template <class Epi, class Sched, bool ALIGN_EPI = false, bool SP2 = false>
; __device__ __forceinline__ void gemm_phase(LAS unsigned char* lds, const Gemm g, const Sched& S, const Epi& E) {
;     ...
;             PG8_WAIT_V(8); PG8_WAIT_L(0); PG8_BAR; PG8_MMA(1, 0, At, B0); PG8_MMA(1, 1, At, B1); PG8_BAR; PG8_SCHED;
;             PG8_LDB(B0, 1, 0); PG8_LDB(B1, 1, 1); PG8_SCHED; PG8_LDA(At, 1, 0); PG8_STAGE(PG8_SA(0, 1), a2 + hsA, voffA);
;             PG8_WAIT_V(8); PG8_WAIT_L(0); PG8_BAR; PG8_MMA(0, 0, At, B0); PG8_MMA(0, 1, At, B1); PG8_BAR; PG8_SCHED;
;             PG8_LDA(At, 1, 1); PG8_STAGE(PG8_SB(1, 0), b3, voffB); PG8_STAGE(PG8_SB(1, 1), b3 + hsB, voffB); PG8_STAGE(PG8_SA(1, 0), a3, voffA);
;             PG8_WAIT_V(8); PG8_WAIT_L(0); PG8_BAR; PG8_MMA(1, 0, At, B0); PG8_MMA(1, 1, At, B1); PG8_BAR; PG8_SCHED;
;     ...
;         if constexpr (ALIGN_EPI) { if (wr == 0) PG8_BAR; }
	v_mfma_f32_16x16x32_bf16 v[0:3], v[176:179], v[208:211], v[0:3]
	v_mfma_f32_16x16x32_bf16 v[0:3], v[180:183], v[212:215], v[0:3]
	s_setprio 0
	s_add_i32 s51, 0, 0x18000
	v_add_u32_e32 v155, s51, v146
	v_xor_b32_e32 v253, 64, v155
	s_add_i32 s52, 0, 0x1c000
	ds_read_b128 v[140:143], v155
	ds_read_b128 v[156:159], v253
	ds_read_b128 v[160:163], v155 offset:2048
	ds_read_b128 v[164:167], v253 offset:2048
	v_add_u32_e32 v155, s52, v146
	v_xor_b32_e32 v253, 64, v155
	ds_read_b128 v[168:171], v155
	ds_read_b128 v[172:175], v253
	ds_read_b128 v[176:179], v155 offset:2048
	ds_read_b128 v[180:183], v253 offset:2048
	s_mov_b32 m0, s26
	s_nop 0
	global_load_lds_dwordx4 v128, s[20:21]
	s_mov_b32 m0, s27
	s_nop 0
	global_load_lds_dwordx4 v130, s[20:21]
	s_add_u32 s20, s20, 0x404000
	s_addc_u32 s21, s21, 0
	s_mov_b32 m0, s30
	ds_read_b128 v[184:187], v151 offset:32768
	ds_read_b128 v[188:191], v250 offset:32768
	ds_read_b128 v[192:195], v151 offset:34816
	ds_read_b128 v[196:199], v250 offset:34816
	ds_read_b128 v[200:203], v151 offset:36864
	ds_read_b128 v[204:207], v250 offset:36864
	ds_read_b128 v[208:211], v151 offset:38912
	ds_read_b128 v[212:215], v250 offset:38912
	global_load_lds_dwordx4 v128, s[20:21]
	s_mov_b32 m0, s31
	s_nop 0
	global_load_lds_dwordx4 v130, s[20:21]
	s_waitcnt vmcnt(8)
	s_waitcnt lgkmcnt(0)
	s_setprio 2
	s_barrier
	v_mfma_f32_16x16x32_bf16 v[124:127], v[140:143], v[184:187], v[124:127]
	v_mfma_f32_16x16x32_bf16 v[124:127], v[156:159], v[188:191], v[124:127]
	v_mfma_f32_16x16x32_bf16 v[120:123], v[160:163], v[184:187], v[120:123]
	v_mfma_f32_16x16x32_bf16 v[120:123], v[164:167], v[188:191], v[120:123]
	v_mfma_f32_16x16x32_bf16 v[108:111], v[140:143], v[192:195], v[108:111]
	v_mfma_f32_16x16x32_bf16 v[108:111], v[156:159], v[196:199], v[108:111]
	v_mfma_f32_16x16x32_bf16 v[104:107], v[160:163], v[192:195], v[104:107]
	v_mfma_f32_16x16x32_bf16 v[104:107], v[164:167], v[196:199], v[104:107]
	v_mfma_f32_16x16x32_bf16 v[92:95], v[140:143], v[200:203], v[92:95]
	v_mfma_f32_16x16x32_bf16 v[92:95], v[156:159], v[204:207], v[92:95]
	v_mfma_f32_16x16x32_bf16 v[88:91], v[160:163], v[200:203], v[88:91]
	v_mfma_f32_16x16x32_bf16 v[88:91], v[164:167], v[204:207], v[88:91]
	v_mfma_f32_16x16x32_bf16 v[76:79], v[140:143], v[208:211], v[76:79]
	v_mfma_f32_16x16x32_bf16 v[76:79], v[156:159], v[212:215], v[76:79]
	v_mfma_f32_16x16x32_bf16 v[72:75], v[160:163], v[208:211], v[72:75]
	v_mfma_f32_16x16x32_bf16 v[72:75], v[164:167], v[212:215], v[72:75]
	s_setprio 0
	s_setprio 2
	v_mfma_f32_16x16x32_bf16 v[116:119], v[168:171], v[184:187], v[116:119]
	v_mfma_f32_16x16x32_bf16 v[116:119], v[172:175], v[188:191], v[116:119]
	v_mfma_f32_16x16x32_bf16 v[112:115], v[176:179], v[184:187], v[112:115]
	v_mfma_f32_16x16x32_bf16 v[112:115], v[180:183], v[188:191], v[112:115]
	v_mfma_f32_16x16x32_bf16 v[100:103], v[168:171], v[192:195], v[100:103]
	v_mfma_f32_16x16x32_bf16 v[100:103], v[172:175], v[196:199], v[100:103]
	v_mfma_f32_16x16x32_bf16 v[96:99], v[176:179], v[192:195], v[96:99]
	v_mfma_f32_16x16x32_bf16 v[96:99], v[180:183], v[196:199], v[96:99]
	v_mfma_f32_16x16x32_bf16 v[84:87], v[168:171], v[200:203], v[84:87]
	v_mfma_f32_16x16x32_bf16 v[84:87], v[172:175], v[204:207], v[84:87]
	v_mfma_f32_16x16x32_bf16 v[80:83], v[176:179], v[200:203], v[80:83]
	v_mfma_f32_16x16x32_bf16 v[80:83], v[180:183], v[204:207], v[80:83]
	v_mfma_f32_16x16x32_bf16 v[68:71], v[168:171], v[208:211], v[68:71]
	v_mfma_f32_16x16x32_bf16 v[68:71], v[172:175], v[212:215], v[68:71]
	s_setprio 3
	s_barrier
	v_mfma_f32_16x16x32_bf16 v[64:67], v[176:179], v[208:211], v[64:67]
	v_mfma_f32_16x16x32_bf16 v[64:67], v[180:183], v[212:215], v[64:67]
	s_setprio 0
	s_add_i32 s20, s51, s25
	s_add_u32 s100, s16, s8
	s_addc_u32 s101, s17, s9
	s_mov_b32 m0, s20
	ds_read_b128 v[184:187], v151 offset:49152
	ds_read_b128 v[188:191], v250 offset:49152
	ds_read_b128 v[192:195], v151 offset:51200
	ds_read_b128 v[196:199], v250 offset:51200
	ds_read_b128 v[200:203], v151 offset:53248
	ds_read_b128 v[204:207], v250 offset:53248
	ds_read_b128 v[208:211], v151 offset:55296
	ds_read_b128 v[212:215], v250 offset:55296
	global_load_lds_dwordx4 v128, s[100:101]
	s_add_i32 m0, s20, 0x2000
	s_add_u32 s16, s16, 0x404080
	s_addc_u32 s17, s17, 0
	s_add_i32 s20, s52, s25
	global_load_lds_dwordx4 v130, s[100:101]
	s_mov_b32 m0, s20
	s_nop 0
	global_load_lds_dwordx4 v128, s[16:17]
	s_add_i32 m0, s20, 0x2000
	s_nop 0
	global_load_lds_dwordx4 v130, s[16:17]
	s_waitcnt vmcnt(6)
	s_waitcnt lgkmcnt(0)
	s_setprio 2
	s_barrier
	v_mfma_f32_16x16x32_bf16 v[60:63], v[140:143], v[184:187], v[60:63]
	v_mfma_f32_16x16x32_bf16 v[60:63], v[156:159], v[188:191], v[60:63]
	v_mfma_f32_16x16x32_bf16 v[56:59], v[160:163], v[184:187], v[56:59]
	v_mfma_f32_16x16x32_bf16 v[56:59], v[164:167], v[188:191], v[56:59]
	v_mfma_f32_16x16x32_bf16 v[44:47], v[140:143], v[192:195], v[44:47]
	v_mfma_f32_16x16x32_bf16 v[44:47], v[156:159], v[196:199], v[44:47]
	v_mfma_f32_16x16x32_bf16 v[40:43], v[160:163], v[192:195], v[40:43]
	v_mfma_f32_16x16x32_bf16 v[40:43], v[164:167], v[196:199], v[40:43]
	v_mfma_f32_16x16x32_bf16 v[28:31], v[140:143], v[200:203], v[28:31]
	v_mfma_f32_16x16x32_bf16 v[28:31], v[156:159], v[204:207], v[28:31]
	v_mfma_f32_16x16x32_bf16 v[24:27], v[160:163], v[200:203], v[24:27]
	v_mfma_f32_16x16x32_bf16 v[24:27], v[164:167], v[204:207], v[24:27]
	v_mfma_f32_16x16x32_bf16 v[12:15], v[140:143], v[208:211], v[12:15]
	v_mfma_f32_16x16x32_bf16 v[12:15], v[156:159], v[212:215], v[12:15]
	v_mfma_f32_16x16x32_bf16 v[8:11], v[160:163], v[208:211], v[8:11]
	v_mfma_f32_16x16x32_bf16 v[8:11], v[164:167], v[212:215], v[8:11]
	s_setprio 0
	s_setprio 2
	v_mfma_f32_16x16x32_bf16 v[52:55], v[168:171], v[184:187], v[52:55]
	v_mfma_f32_16x16x32_bf16 v[52:55], v[172:175], v[188:191], v[52:55]
	v_mfma_f32_16x16x32_bf16 v[48:51], v[176:179], v[184:187], v[48:51]
	v_mfma_f32_16x16x32_bf16 v[48:51], v[180:183], v[188:191], v[48:51]
	v_mfma_f32_16x16x32_bf16 v[36:39], v[168:171], v[192:195], v[36:39]
	v_mfma_f32_16x16x32_bf16 v[36:39], v[172:175], v[196:199], v[36:39]
	v_mfma_f32_16x16x32_bf16 v[32:35], v[176:179], v[192:195], v[32:35]
	v_mfma_f32_16x16x32_bf16 v[32:35], v[180:183], v[196:199], v[32:35]
	v_mfma_f32_16x16x32_bf16 v[20:23], v[168:171], v[200:203], v[20:23]
	v_mfma_f32_16x16x32_bf16 v[20:23], v[172:175], v[204:207], v[20:23]
	v_mfma_f32_16x16x32_bf16 v[16:19], v[176:179], v[200:203], v[16:19]
	v_mfma_f32_16x16x32_bf16 v[16:19], v[180:183], v[204:207], v[16:19]
	v_mfma_f32_16x16x32_bf16 v[4:7], v[168:171], v[208:211], v[4:7]
	v_mfma_f32_16x16x32_bf16 v[4:7], v[172:175], v[212:215], v[4:7]
	s_setprio 3
	s_barrier
	v_mfma_f32_16x16x32_bf16 v[0:3], v[176:179], v[208:211], v[0:3]
	v_mfma_f32_16x16x32_bf16 v[0:3], v[180:183], v[212:215], v[0:3]
	s_setprio 0
	s_add_i32 s50, s50, 2
	s_add_u32 s14, s14, 0x100
	s_addc_u32 s15, s15, 0
	s_add_u32 s48, s48, 0x100
	s_addc_u32 s49, s49, 0
	s_cmpk_gt_u32 s50, 0xfd
	s_cbranch_scc0 .LBB0_350
	s_and_b64 vcc, exec, s[10:11]
	s_cbranch_vccz .LBB0_353
	s_barrier
